# silu x/(1+exp(-x)) in both in-projection epilogues computed as x*rcp(1+exp(-x)) (f32 v_rcp_f32) instead of the 11-instruction IEEE division expansion
# speedup vs baseline: 1.0684x; 1.0174x over previous
.LBB0_147:
	s_lshl_b32 s29, s8, 8
	v_or_b32_e32 v174, s29, v218
	v_lshlrev_b64 v[214:215], 13, v[176:177]
	v_pk_mul_f32 v[158:159], v[158:159], v[212:213] op_sel_hi:[1,0]
	v_pk_mul_f32 v[156:157], v[156:157], v[212:213] op_sel_hi:[1,0]
	v_pk_mul_f32 v[154:155], v[154:155], v[212:213] op_sel_hi:[1,0]
	v_pk_mul_f32 v[152:153], v[152:153], v[212:213] op_sel_hi:[1,0]
	v_lshl_add_u64 v[214:215], s[20:21], 0, v[214:215]
	v_cmp_lt_i32_e64 s[10:11], s97, v174
	s_and_saveexec_b64 s[0:1], s[10:11]
	s_xor_b64 s[2:3], exec, s[0:1]
	s_cbranch_execz .LBB0_151
	s_cmpk_lt_u32 s29, 0x1000
	s_mov_b64 s[0:1], 0
	s_cbranch_scc1 .LBB0_150
	v_mul_f32_e32 v175, 0xbfb8aa3b, v152
	v_exp_f32_e32 v222, v175
	v_mul_f32_e32 v175, 0xbfb8aa3b, v153
	v_exp_f32_e32 v223, v175
	v_mul_f32_e32 v175, 0xbfb8aa3b, v154
	v_exp_f32_e32 v224, v175
	v_mul_f32_e32 v175, 0xbfb8aa3b, v155
	v_exp_f32_e32 v225, v175
	v_pk_add_f32 v[222:223], v[222:223], 1.0 op_sel_hi:[1,0]
	v_pk_add_f32 v[224:225], v[224:225], 1.0 op_sel_hi:[1,0]
	s_nop 0
	v_rcp_f32_e32 v179, v225
	s_nop 0
	v_mul_f32_e32 v155, v155, v179
	v_rcp_f32_e32 v179, v224
	s_nop 0
	v_mul_f32_e32 v154, v154, v179
	v_rcp_f32_e32 v179, v223
	s_nop 0
	v_mul_f32_e32 v153, v153, v179
	v_rcp_f32_e32 v179, v222
	s_mov_b64 s[0:1], 0x400
	v_mul_f32_e32 v152, v152, v179

.LBB0_151:
	s_andn2_saveexec_b64 s[2:3], s[2:3]
	s_cbranch_execz .LBB0_155
	v_cmp_lt_i32_e32 vcc, s83, v174
	s_and_saveexec_b64 s[8:9], vcc
	s_cbranch_execz .LBB0_154
	v_mul_f32_e32 v175, 0xbfb8aa3b, v156
	v_exp_f32_e32 v222, v175
	v_mul_f32_e32 v175, 0xbfb8aa3b, v152
	v_exp_f32_e32 v224, v175
	v_mul_f32_e32 v175, 0xbfb8aa3b, v157
	v_exp_f32_e32 v223, v175
	v_mul_f32_e32 v175, 0xbfb8aa3b, v153
	v_exp_f32_e32 v225, v175
	v_mul_f32_e32 v175, 0xbfb8aa3b, v158
	v_exp_f32_e32 v226, v175
	v_mul_f32_e32 v175, 0xbfb8aa3b, v154
	v_exp_f32_e32 v228, v175
	v_mul_f32_e32 v175, 0xbfb8aa3b, v159
	v_exp_f32_e32 v227, v175
	v_pk_add_f32 v[222:223], v[222:223], 1.0 op_sel_hi:[1,0]
	v_pk_add_f32 v[226:227], v[226:227], 1.0 op_sel_hi:[1,0]
	s_nop 0
	v_rcp_f32_e32 v179, v227
	s_nop 0
	v_mul_f32_e32 v159, v159, v179
	v_rcp_f32_e32 v179, v226
	s_nop 0
	v_mul_f32_e32 v158, v158, v179
	v_rcp_f32_e32 v179, v223
	s_nop 0
	v_mul_f32_e32 v157, v157, v179
	v_rcp_f32_e32 v179, v222
	s_nop 0
	v_mul_f32_e32 v156, v156, v179
	v_mul_f32_e32 v175, 0xbfb8aa3b, v155
	v_exp_f32_e32 v229, v175
	v_pk_add_f32 v[222:223], v[224:225], 1.0 op_sel_hi:[1,0]
	v_pk_add_f32 v[224:225], v[228:229], 1.0 op_sel_hi:[1,0]
	s_nop 0
	v_rcp_f32_e32 v179, v225
	s_nop 0
	v_mul_f32_e32 v155, v155, v179
	v_rcp_f32_e32 v179, v224
	s_nop 0
	v_mul_f32_e32 v154, v154, v179
	v_rcp_f32_e32 v179, v223
	s_nop 0
	v_mul_f32_e32 v153, v153, v179
	v_rcp_f32_e32 v179, v222
	s_nop 0
	v_mul_f32_e32 v152, v152, v179

.LBB0_155:
	s_or_b64 exec, exec, s[2:3]
	v_mov_b32_e32 v213, v212
	v_or_b32_e32 v152, 0x80, v174
	v_mov_b32_e32 v154, v212
	v_mov_b32_e32 v155, v212
	v_pk_mul_f32 v[150:151], v[150:151], v[154:155]
	v_pk_mul_f32 v[148:149], v[148:149], v[212:213]
	v_pk_mul_f32 v[146:147], v[146:147], v[154:155]
	v_pk_mul_f32 v[144:145], v[144:145], v[212:213]
	v_cmp_lt_i32_e64 s[8:9], s97, v152
	s_and_saveexec_b64 s[0:1], s[8:9]
	s_xor_b64 s[2:3], exec, s[0:1]
	s_cbranch_execz .LBB0_159
	s_cmpk_lt_u32 s29, 0x1000
	s_mov_b64 s[0:1], 0
	s_cbranch_scc1 .LBB0_158
	v_mul_f32_e32 v153, 0xbfb8aa3b, v144
	v_exp_f32_e32 v154, v153
	v_mul_f32_e32 v153, 0xbfb8aa3b, v145
	v_exp_f32_e32 v155, v153
	v_mul_f32_e32 v153, 0xbfb8aa3b, v146
	v_exp_f32_e32 v156, v153
	v_mul_f32_e32 v153, 0xbfb8aa3b, v147
	v_exp_f32_e32 v157, v153
	v_pk_add_f32 v[154:155], v[154:155], 1.0 op_sel_hi:[1,0]
	v_pk_add_f32 v[156:157], v[156:157], 1.0 op_sel_hi:[1,0]
	s_nop 0
	v_rcp_f32_e32 v158, v157
	s_nop 0
	v_mul_f32_e32 v147, v147, v158
	v_rcp_f32_e32 v157, v156
	s_nop 0
	v_mul_f32_e32 v146, v146, v157
	v_rcp_f32_e32 v156, v155
	s_nop 0
	v_mul_f32_e32 v145, v145, v156
	v_rcp_f32_e32 v155, v154
	s_mov_b64 s[0:1], 0x400
	v_mul_f32_e32 v144, v144, v155

.LBB0_159:
	s_andn2_saveexec_b64 s[2:3], s[2:3]
	s_cbranch_execz .LBB0_163
	v_cmp_lt_i32_e32 vcc, s83, v152
	s_and_saveexec_b64 s[42:43], vcc
	s_cbranch_execz .LBB0_162
	v_mul_f32_e32 v153, 0xbfb8aa3b, v148
	v_exp_f32_e32 v154, v153
	v_mul_f32_e32 v153, 0xbfb8aa3b, v144
	v_exp_f32_e32 v156, v153
	v_mul_f32_e32 v153, 0xbfb8aa3b, v149
	v_exp_f32_e32 v155, v153
	v_mul_f32_e32 v153, 0xbfb8aa3b, v145
	v_exp_f32_e32 v157, v153
	v_mul_f32_e32 v153, 0xbfb8aa3b, v150
	v_exp_f32_e32 v158, v153
	v_mul_f32_e32 v153, 0xbfb8aa3b, v146
	v_exp_f32_e32 v212, v153
	v_mul_f32_e32 v153, 0xbfb8aa3b, v151
	v_exp_f32_e32 v159, v153
	v_pk_add_f32 v[154:155], v[154:155], 1.0 op_sel_hi:[1,0]
	v_pk_add_f32 v[158:159], v[158:159], 1.0 op_sel_hi:[1,0]
	s_nop 0
	v_rcp_f32_e32 v175, v159
	s_nop 0
	v_mul_f32_e32 v151, v151, v175
	v_rcp_f32_e32 v159, v158
	s_nop 0
	v_mul_f32_e32 v150, v150, v159
	v_rcp_f32_e32 v158, v155
	s_nop 0
	v_mul_f32_e32 v149, v149, v158
	v_rcp_f32_e32 v155, v154
	s_nop 0
	v_mul_f32_e32 v148, v148, v155
	v_mul_f32_e32 v153, 0xbfb8aa3b, v147
	v_exp_f32_e32 v213, v153
	v_pk_add_f32 v[154:155], v[156:157], 1.0 op_sel_hi:[1,0]
	v_pk_add_f32 v[156:157], v[212:213], 1.0 op_sel_hi:[1,0]
	s_nop 0
	v_rcp_f32_e32 v158, v157
	s_nop 0
	v_mul_f32_e32 v147, v147, v158
	v_rcp_f32_e32 v157, v156
	s_nop 0
	v_mul_f32_e32 v146, v146, v157
	v_rcp_f32_e32 v156, v155
	s_nop 0
	v_mul_f32_e32 v145, v145, v156
	v_rcp_f32_e32 v155, v154
	s_nop 0
	v_mul_f32_e32 v144, v144, v155

.LBB0_163:
	s_or_b64 exec, exec, s[2:3]
	v_or_b32_e32 v144, 16, v176
	v_ashrrev_i32_e32 v145, 31, v144
	v_lshlrev_b64 v[144:145], 13, v[144:145]
	v_pk_mul_f32 v[142:143], v[142:143], v[210:211] op_sel_hi:[1,0]
	v_pk_mul_f32 v[140:141], v[140:141], v[210:211] op_sel_hi:[1,0]
	v_pk_mul_f32 v[138:139], v[138:139], v[210:211] op_sel_hi:[1,0]
	v_pk_mul_f32 v[136:137], v[136:137], v[210:211] op_sel_hi:[1,0]
	v_lshl_add_u64 v[144:145], s[20:21], 0, v[144:145]
	s_and_saveexec_b64 s[0:1], s[10:11]
	s_xor_b64 s[2:3], exec, s[0:1]
	s_cbranch_execz .LBB0_167
	s_cmpk_lt_u32 s29, 0x1000
	s_mov_b64 s[0:1], 0
	s_cbranch_scc1 .LBB0_166
	v_mul_f32_e32 v148, 0xbfb8aa3b, v138
	v_mul_f32_e32 v149, 0xbfb8aa3b, v139
	v_exp_f32_e32 v148, v148
	v_exp_f32_e32 v149, v149
	v_mul_f32_e32 v146, 0xbfb8aa3b, v136
	v_mul_f32_e32 v147, 0xbfb8aa3b, v137
	v_exp_f32_e32 v146, v146
	v_pk_add_f32 v[148:149], v[148:149], 1.0 op_sel_hi:[1,0]
	v_exp_f32_e32 v147, v147
	v_rcp_f32_e32 v151, v149
	v_pk_add_f32 v[146:147], v[146:147], 1.0 op_sel_hi:[1,0]
	v_mul_f32_e32 v139, v139, v151
	v_rcp_f32_e32 v150, v148
	s_nop 0
	v_mul_f32_e32 v138, v138, v150
	v_rcp_f32_e32 v149, v147
	s_nop 0
	v_mul_f32_e32 v137, v137, v149
	v_rcp_f32_e32 v148, v146
	s_mov_b64 s[0:1], 0x400
	v_mul_f32_e32 v136, v136, v148

.LBB0_167:
	s_andn2_saveexec_b64 s[2:3], s[2:3]
	s_cbranch_execz .LBB0_171
	v_cmp_lt_i32_e32 vcc, s83, v174
	s_and_saveexec_b64 s[42:43], vcc
	s_cbranch_execz .LBB0_170
	v_mul_f32_e32 v151, 0xbfb8aa3b, v138
	v_mul_f32_e32 v150, 0xbfb8aa3b, v142
	v_exp_f32_e32 v154, v151
	v_mul_f32_e32 v151, 0xbfb8aa3b, v143
	v_exp_f32_e32 v150, v150
	v_exp_f32_e32 v151, v151
	v_mul_f32_e32 v147, 0xbfb8aa3b, v136
	v_mul_f32_e32 v146, 0xbfb8aa3b, v140
	v_exp_f32_e32 v148, v147
	v_pk_add_f32 v[150:151], v[150:151], 1.0 op_sel_hi:[1,0]
	v_mul_f32_e32 v147, 0xbfb8aa3b, v141
	v_rcp_f32_e32 v155, v151
	v_exp_f32_e32 v146, v146
	v_exp_f32_e32 v147, v147
	v_mul_f32_e32 v149, 0xbfb8aa3b, v137
	v_mul_f32_e32 v143, v143, v155
	v_rcp_f32_e32 v153, v150
	v_pk_add_f32 v[146:147], v[146:147], 1.0 op_sel_hi:[1,0]
	v_exp_f32_e32 v149, v149
	v_mul_f32_e32 v142, v142, v153
	v_rcp_f32_e32 v151, v147
	s_nop 0
	v_mul_f32_e32 v141, v141, v151
	v_rcp_f32_e32 v150, v146
	s_nop 0
	v_mul_f32_e32 v140, v140, v150
	v_mul_f32_e32 v146, 0xbfb8aa3b, v139
	v_exp_f32_e32 v155, v146
	v_pk_add_f32 v[146:147], v[148:149], 1.0 op_sel_hi:[1,0]
	v_pk_add_f32 v[148:149], v[154:155], 1.0 op_sel_hi:[1,0]
	s_nop 0
	v_rcp_f32_e32 v151, v149
	s_nop 0
	v_mul_f32_e32 v139, v139, v151
	v_rcp_f32_e32 v150, v148
	s_nop 0
	v_mul_f32_e32 v138, v138, v150
	v_rcp_f32_e32 v149, v147
	s_nop 0
	v_mul_f32_e32 v137, v137, v149
	v_rcp_f32_e32 v148, v146
	s_nop 0
	v_mul_f32_e32 v136, v136, v148

.LBB0_171:
	s_or_b64 exec, exec, s[2:3]
	v_mov_b32_e32 v211, v210
	v_mov_b32_e32 v136, v210
	v_mov_b32_e32 v137, v210
	v_pk_mul_f32 v[134:135], v[134:135], v[136:137]
	v_pk_mul_f32 v[132:133], v[132:133], v[210:211]
	v_pk_mul_f32 v[130:131], v[130:131], v[136:137]
	v_pk_mul_f32 v[128:129], v[128:129], v[210:211]
	s_and_saveexec_b64 s[0:1], s[8:9]
	s_xor_b64 s[2:3], exec, s[0:1]
	s_cbranch_execz .LBB0_175
	s_cmpk_lt_u32 s29, 0x1000
	s_mov_b64 s[0:1], 0
	s_cbranch_scc1 .LBB0_174
	v_mul_f32_e32 v138, 0xbfb8aa3b, v130
	v_mul_f32_e32 v139, 0xbfb8aa3b, v131
	v_exp_f32_e32 v138, v138
	v_exp_f32_e32 v139, v139
	v_mul_f32_e32 v136, 0xbfb8aa3b, v128
	v_mul_f32_e32 v137, 0xbfb8aa3b, v129
	v_exp_f32_e32 v136, v136
	v_pk_add_f32 v[138:139], v[138:139], 1.0 op_sel_hi:[1,0]
	v_exp_f32_e32 v137, v137
	v_rcp_f32_e32 v141, v139
	v_pk_add_f32 v[136:137], v[136:137], 1.0 op_sel_hi:[1,0]
	v_mul_f32_e32 v131, v131, v141
	v_rcp_f32_e32 v140, v138
	s_nop 0
	v_mul_f32_e32 v130, v130, v140
	v_rcp_f32_e32 v139, v137
	s_nop 0
	v_mul_f32_e32 v129, v129, v139
	v_rcp_f32_e32 v138, v136
	s_mov_b64 s[0:1], 0x400
	v_mul_f32_e32 v128, v128, v138

.LBB0_175:
	s_andn2_saveexec_b64 s[2:3], s[2:3]
	s_cbranch_execz .LBB0_179
	v_cmp_lt_i32_e32 vcc, s83, v152
	s_and_saveexec_b64 s[42:43], vcc
	s_cbranch_execz .LBB0_178
	v_mul_f32_e32 v141, 0xbfb8aa3b, v130
	v_mul_f32_e32 v140, 0xbfb8aa3b, v134
	v_exp_f32_e32 v142, v141
	v_mul_f32_e32 v141, 0xbfb8aa3b, v135
	v_exp_f32_e32 v140, v140
	v_exp_f32_e32 v141, v141
	v_mul_f32_e32 v137, 0xbfb8aa3b, v128
	v_mul_f32_e32 v136, 0xbfb8aa3b, v132
	v_exp_f32_e32 v138, v137
	v_pk_add_f32 v[140:141], v[140:141], 1.0 op_sel_hi:[1,0]
	v_mul_f32_e32 v137, 0xbfb8aa3b, v133
	v_rcp_f32_e32 v146, v141
	v_exp_f32_e32 v136, v136
	v_exp_f32_e32 v137, v137
	v_mul_f32_e32 v139, 0xbfb8aa3b, v129
	v_mul_f32_e32 v135, v135, v146
	v_rcp_f32_e32 v143, v140
	v_pk_add_f32 v[136:137], v[136:137], 1.0 op_sel_hi:[1,0]
	v_exp_f32_e32 v139, v139
	v_mul_f32_e32 v134, v134, v143
	v_rcp_f32_e32 v141, v137
	s_nop 0
	v_mul_f32_e32 v133, v133, v141
	v_rcp_f32_e32 v140, v136
	s_nop 0
	v_mul_f32_e32 v132, v132, v140
	v_mul_f32_e32 v136, 0xbfb8aa3b, v131
	v_exp_f32_e32 v143, v136
	v_pk_add_f32 v[136:137], v[138:139], 1.0 op_sel_hi:[1,0]
	v_pk_add_f32 v[138:139], v[142:143], 1.0 op_sel_hi:[1,0]
	s_nop 0
	v_rcp_f32_e32 v141, v139
	s_nop 0
	v_mul_f32_e32 v131, v131, v141
	v_rcp_f32_e32 v140, v138
	s_nop 0
	v_mul_f32_e32 v130, v130, v140
	v_rcp_f32_e32 v139, v137
	s_nop 0
	v_mul_f32_e32 v129, v129, v139
	v_rcp_f32_e32 v138, v136
	s_nop 0
	v_mul_f32_e32 v128, v128, v138

.LBB0_179:
	s_or_b64 exec, exec, s[2:3]
	v_or_b32_e32 v128, 32, v176
	v_ashrrev_i32_e32 v129, 31, v128
	v_lshlrev_b64 v[128:129], 13, v[128:129]
	v_pk_mul_f32 v[126:127], v[126:127], v[208:209] op_sel_hi:[1,0]
	v_pk_mul_f32 v[124:125], v[124:125], v[208:209] op_sel_hi:[1,0]
	v_pk_mul_f32 v[122:123], v[122:123], v[208:209] op_sel_hi:[1,0]
	v_pk_mul_f32 v[120:121], v[120:121], v[208:209] op_sel_hi:[1,0]
	v_lshl_add_u64 v[128:129], s[20:21], 0, v[128:129]
	s_and_saveexec_b64 s[0:1], s[10:11]
	s_xor_b64 s[2:3], exec, s[0:1]
	s_cbranch_execz .LBB0_183
	s_cmpk_lt_u32 s29, 0x1000
	s_mov_b64 s[0:1], 0
	s_cbranch_scc1 .LBB0_182
	v_mul_f32_e32 v132, 0xbfb8aa3b, v122
	v_mul_f32_e32 v133, 0xbfb8aa3b, v123
	v_exp_f32_e32 v132, v132
	v_exp_f32_e32 v133, v133
	v_mul_f32_e32 v130, 0xbfb8aa3b, v120
	v_mul_f32_e32 v131, 0xbfb8aa3b, v121
	v_exp_f32_e32 v130, v130
	v_pk_add_f32 v[132:133], v[132:133], 1.0 op_sel_hi:[1,0]
	v_exp_f32_e32 v131, v131
	v_rcp_f32_e32 v135, v133
	v_pk_add_f32 v[130:131], v[130:131], 1.0 op_sel_hi:[1,0]
	v_mul_f32_e32 v123, v123, v135
	v_rcp_f32_e32 v134, v132
	s_nop 0
	v_mul_f32_e32 v122, v122, v134
	v_rcp_f32_e32 v133, v131
	s_nop 0
	v_mul_f32_e32 v121, v121, v133
	v_rcp_f32_e32 v132, v130
	s_mov_b64 s[0:1], 0x400
	v_mul_f32_e32 v120, v120, v132

.LBB0_183:
	s_andn2_saveexec_b64 s[2:3], s[2:3]
	s_cbranch_execz .LBB0_187
	v_cmp_lt_i32_e32 vcc, s83, v174
	s_and_saveexec_b64 s[42:43], vcc
	s_cbranch_execz .LBB0_186
	v_mul_f32_e32 v135, 0xbfb8aa3b, v122
	v_mul_f32_e32 v134, 0xbfb8aa3b, v126
	v_exp_f32_e32 v136, v135
	v_mul_f32_e32 v135, 0xbfb8aa3b, v127
	v_exp_f32_e32 v134, v134
	v_exp_f32_e32 v135, v135
	v_mul_f32_e32 v131, 0xbfb8aa3b, v120
	v_mul_f32_e32 v130, 0xbfb8aa3b, v124
	v_exp_f32_e32 v132, v131
	v_pk_add_f32 v[134:135], v[134:135], 1.0 op_sel_hi:[1,0]
	v_mul_f32_e32 v131, 0xbfb8aa3b, v125
	v_rcp_f32_e32 v138, v135
	v_exp_f32_e32 v130, v130
	v_exp_f32_e32 v131, v131
	v_mul_f32_e32 v133, 0xbfb8aa3b, v121
	v_mul_f32_e32 v127, v127, v138
	v_rcp_f32_e32 v137, v134
	v_pk_add_f32 v[130:131], v[130:131], 1.0 op_sel_hi:[1,0]
	v_exp_f32_e32 v133, v133
	v_mul_f32_e32 v126, v126, v137
	v_rcp_f32_e32 v135, v131
	s_nop 0
	v_mul_f32_e32 v125, v125, v135
	v_rcp_f32_e32 v134, v130
	s_nop 0
	v_mul_f32_e32 v124, v124, v134
	v_mul_f32_e32 v130, 0xbfb8aa3b, v123
	v_exp_f32_e32 v137, v130
	v_pk_add_f32 v[130:131], v[132:133], 1.0 op_sel_hi:[1,0]
	v_pk_add_f32 v[132:133], v[136:137], 1.0 op_sel_hi:[1,0]
	s_nop 0
	v_rcp_f32_e32 v135, v133
	s_nop 0
	v_mul_f32_e32 v123, v123, v135
	v_rcp_f32_e32 v134, v132
	s_nop 0
	v_mul_f32_e32 v122, v122, v134
	v_rcp_f32_e32 v133, v131
	s_nop 0
	v_mul_f32_e32 v121, v121, v133
	v_rcp_f32_e32 v132, v130
	s_nop 0
	v_mul_f32_e32 v120, v120, v132

.LBB0_187:
	s_or_b64 exec, exec, s[2:3]
	v_mov_b32_e32 v209, v208
	v_mov_b32_e32 v120, v208
	v_mov_b32_e32 v121, v208
	v_pk_mul_f32 v[118:119], v[118:119], v[120:121]
	v_pk_mul_f32 v[116:117], v[116:117], v[208:209]
	v_pk_mul_f32 v[114:115], v[114:115], v[120:121]
	v_pk_mul_f32 v[112:113], v[112:113], v[208:209]
	s_and_saveexec_b64 s[0:1], s[8:9]
	s_xor_b64 s[2:3], exec, s[0:1]
	s_cbranch_execz .LBB0_191
	s_cmpk_lt_u32 s29, 0x1000
	s_mov_b64 s[0:1], 0
	s_cbranch_scc1 .LBB0_190
	v_mul_f32_e32 v122, 0xbfb8aa3b, v114
	v_mul_f32_e32 v123, 0xbfb8aa3b, v115
	v_exp_f32_e32 v122, v122
	v_exp_f32_e32 v123, v123
	v_mul_f32_e32 v120, 0xbfb8aa3b, v112
	v_mul_f32_e32 v121, 0xbfb8aa3b, v113
	v_exp_f32_e32 v120, v120
	v_pk_add_f32 v[122:123], v[122:123], 1.0 op_sel_hi:[1,0]
	v_exp_f32_e32 v121, v121
	v_rcp_f32_e32 v125, v123
	v_pk_add_f32 v[120:121], v[120:121], 1.0 op_sel_hi:[1,0]
	v_mul_f32_e32 v115, v115, v125
	v_rcp_f32_e32 v124, v122
	s_nop 0
	v_mul_f32_e32 v114, v114, v124
	v_rcp_f32_e32 v123, v121
	s_nop 0
	v_mul_f32_e32 v113, v113, v123
	v_rcp_f32_e32 v122, v120
	s_mov_b64 s[0:1], 0x400
	v_mul_f32_e32 v112, v112, v122

.LBB0_191:
	s_andn2_saveexec_b64 s[2:3], s[2:3]
	s_cbranch_execz .LBB0_195
	v_cmp_lt_i32_e32 vcc, s83, v152
	s_and_saveexec_b64 s[42:43], vcc
	s_cbranch_execz .LBB0_194
	v_mul_f32_e32 v125, 0xbfb8aa3b, v114
	v_mul_f32_e32 v124, 0xbfb8aa3b, v118
	v_exp_f32_e32 v126, v125
	v_mul_f32_e32 v125, 0xbfb8aa3b, v119
	v_exp_f32_e32 v124, v124
	v_exp_f32_e32 v125, v125
	v_mul_f32_e32 v121, 0xbfb8aa3b, v112
	v_mul_f32_e32 v120, 0xbfb8aa3b, v116
	v_exp_f32_e32 v122, v121
	v_pk_add_f32 v[124:125], v[124:125], 1.0 op_sel_hi:[1,0]
	v_mul_f32_e32 v121, 0xbfb8aa3b, v117
	v_rcp_f32_e32 v130, v125
	v_exp_f32_e32 v120, v120
	v_exp_f32_e32 v121, v121
	v_mul_f32_e32 v123, 0xbfb8aa3b, v113
	v_mul_f32_e32 v119, v119, v130
	v_rcp_f32_e32 v127, v124
	v_pk_add_f32 v[120:121], v[120:121], 1.0 op_sel_hi:[1,0]
	v_exp_f32_e32 v123, v123
	v_mul_f32_e32 v118, v118, v127
	v_rcp_f32_e32 v125, v121
	s_nop 0
	v_mul_f32_e32 v117, v117, v125
	v_rcp_f32_e32 v124, v120
	s_nop 0
	v_mul_f32_e32 v116, v116, v124
	v_mul_f32_e32 v120, 0xbfb8aa3b, v115
	v_exp_f32_e32 v127, v120
	v_pk_add_f32 v[120:121], v[122:123], 1.0 op_sel_hi:[1,0]
	v_pk_add_f32 v[122:123], v[126:127], 1.0 op_sel_hi:[1,0]
	s_nop 0
	v_rcp_f32_e32 v125, v123
	s_nop 0
	v_mul_f32_e32 v115, v115, v125
	v_rcp_f32_e32 v124, v122
	s_nop 0
	v_mul_f32_e32 v114, v114, v124
	v_rcp_f32_e32 v123, v121
	s_nop 0
	v_mul_f32_e32 v113, v113, v123
	v_rcp_f32_e32 v122, v120
	s_nop 0
	v_mul_f32_e32 v112, v112, v122

.LBB0_195:
	s_or_b64 exec, exec, s[2:3]
	v_or_b32_e32 v112, 48, v176
	v_ashrrev_i32_e32 v113, 31, v112
	v_lshlrev_b64 v[112:113], 13, v[112:113]
	v_pk_mul_f32 v[110:111], v[110:111], v[206:207] op_sel_hi:[1,0]
	v_pk_mul_f32 v[108:109], v[108:109], v[206:207] op_sel_hi:[1,0]
	v_pk_mul_f32 v[106:107], v[106:107], v[206:207] op_sel_hi:[1,0]
	v_pk_mul_f32 v[104:105], v[104:105], v[206:207] op_sel_hi:[1,0]
	v_lshl_add_u64 v[112:113], s[20:21], 0, v[112:113]
	s_and_saveexec_b64 s[0:1], s[10:11]
	s_xor_b64 s[2:3], exec, s[0:1]
	s_cbranch_execz .LBB0_199
	s_cmpk_lt_u32 s29, 0x1000
	s_mov_b64 s[0:1], 0
	s_cbranch_scc1 .LBB0_198
	v_mul_f32_e32 v116, 0xbfb8aa3b, v106
	v_mul_f32_e32 v117, 0xbfb8aa3b, v107
	v_exp_f32_e32 v116, v116
	v_exp_f32_e32 v117, v117
	v_mul_f32_e32 v114, 0xbfb8aa3b, v104
	v_mul_f32_e32 v115, 0xbfb8aa3b, v105
	v_exp_f32_e32 v114, v114
	v_pk_add_f32 v[116:117], v[116:117], 1.0 op_sel_hi:[1,0]
	v_exp_f32_e32 v115, v115
	v_rcp_f32_e32 v119, v117
	v_pk_add_f32 v[114:115], v[114:115], 1.0 op_sel_hi:[1,0]
	v_mul_f32_e32 v107, v107, v119
	v_rcp_f32_e32 v118, v116
	s_nop 0
	v_mul_f32_e32 v106, v106, v118
	v_rcp_f32_e32 v117, v115
	s_nop 0
	v_mul_f32_e32 v105, v105, v117
	v_rcp_f32_e32 v116, v114
	s_mov_b64 s[0:1], 0x400
	v_mul_f32_e32 v104, v104, v116

.LBB0_199:
	s_andn2_saveexec_b64 s[2:3], s[2:3]
	s_cbranch_execz .LBB0_203
	v_cmp_lt_i32_e32 vcc, s83, v174
	s_and_saveexec_b64 s[42:43], vcc
	s_cbranch_execz .LBB0_202
	v_mul_f32_e32 v119, 0xbfb8aa3b, v106
	v_mul_f32_e32 v118, 0xbfb8aa3b, v110
	v_exp_f32_e32 v120, v119
	v_mul_f32_e32 v119, 0xbfb8aa3b, v111
	v_exp_f32_e32 v118, v118
	v_exp_f32_e32 v119, v119
	v_mul_f32_e32 v115, 0xbfb8aa3b, v104
	v_mul_f32_e32 v114, 0xbfb8aa3b, v108
	v_exp_f32_e32 v116, v115
	v_pk_add_f32 v[118:119], v[118:119], 1.0 op_sel_hi:[1,0]
	v_mul_f32_e32 v115, 0xbfb8aa3b, v109
	v_rcp_f32_e32 v122, v119
	v_exp_f32_e32 v114, v114
	v_exp_f32_e32 v115, v115
	v_mul_f32_e32 v117, 0xbfb8aa3b, v105
	v_mul_f32_e32 v111, v111, v122
	v_rcp_f32_e32 v121, v118
	v_pk_add_f32 v[114:115], v[114:115], 1.0 op_sel_hi:[1,0]
	v_exp_f32_e32 v117, v117
	v_mul_f32_e32 v110, v110, v121
	v_rcp_f32_e32 v119, v115
	s_nop 0
	v_mul_f32_e32 v109, v109, v119
	v_rcp_f32_e32 v118, v114
	s_nop 0
	v_mul_f32_e32 v108, v108, v118
	v_mul_f32_e32 v114, 0xbfb8aa3b, v107
	v_exp_f32_e32 v121, v114
	v_pk_add_f32 v[114:115], v[116:117], 1.0 op_sel_hi:[1,0]
	v_pk_add_f32 v[116:117], v[120:121], 1.0 op_sel_hi:[1,0]
	s_nop 0
	v_rcp_f32_e32 v119, v117
	s_nop 0
	v_mul_f32_e32 v107, v107, v119
	v_rcp_f32_e32 v118, v116
	s_nop 0
	v_mul_f32_e32 v106, v106, v118
	v_rcp_f32_e32 v117, v115
	s_nop 0
	v_mul_f32_e32 v105, v105, v117
	v_rcp_f32_e32 v116, v114
	s_nop 0
	v_mul_f32_e32 v104, v104, v116

.LBB0_203:
	s_or_b64 exec, exec, s[2:3]
	v_mov_b32_e32 v207, v206
	v_mov_b32_e32 v104, v206
	v_mov_b32_e32 v105, v206
	v_pk_mul_f32 v[98:99], v[98:99], v[104:105]
	v_pk_mul_f32 v[96:97], v[96:97], v[206:207]
	v_pk_mul_f32 v[94:95], v[94:95], v[104:105]
	v_pk_mul_f32 v[92:93], v[92:93], v[206:207]
	s_and_saveexec_b64 s[0:1], s[8:9]
	s_xor_b64 s[2:3], exec, s[0:1]
	s_cbranch_execz .LBB0_207
	s_cmpk_lt_u32 s29, 0x1000
	s_mov_b64 s[0:1], 0
	s_cbranch_scc1 .LBB0_206
	v_mul_f32_e32 v106, 0xbfb8aa3b, v94
	v_mul_f32_e32 v107, 0xbfb8aa3b, v95
	v_exp_f32_e32 v106, v106
	v_exp_f32_e32 v107, v107
	v_mul_f32_e32 v104, 0xbfb8aa3b, v92
	v_mul_f32_e32 v105, 0xbfb8aa3b, v93
	v_exp_f32_e32 v104, v104
	v_pk_add_f32 v[106:107], v[106:107], 1.0 op_sel_hi:[1,0]
	v_exp_f32_e32 v105, v105
	v_rcp_f32_e32 v109, v107
	v_pk_add_f32 v[104:105], v[104:105], 1.0 op_sel_hi:[1,0]
	v_mul_f32_e32 v95, v95, v109
	v_rcp_f32_e32 v108, v106
	s_nop 0
	v_mul_f32_e32 v94, v94, v108
	v_rcp_f32_e32 v107, v105
	s_nop 0
	v_mul_f32_e32 v93, v93, v107
	v_rcp_f32_e32 v106, v104
	s_mov_b64 s[0:1], 0x400
	v_mul_f32_e32 v92, v92, v106

.LBB0_207:
	s_andn2_saveexec_b64 s[2:3], s[2:3]
	s_cbranch_execz .LBB0_211
	v_cmp_lt_i32_e32 vcc, s83, v152
	s_and_saveexec_b64 s[42:43], vcc
	s_cbranch_execz .LBB0_210
	v_mul_f32_e32 v109, 0xbfb8aa3b, v94
	v_mul_f32_e32 v108, 0xbfb8aa3b, v98
	v_exp_f32_e32 v110, v109
	v_mul_f32_e32 v109, 0xbfb8aa3b, v99
	v_exp_f32_e32 v108, v108
	v_exp_f32_e32 v109, v109
	v_mul_f32_e32 v105, 0xbfb8aa3b, v92
	v_mul_f32_e32 v104, 0xbfb8aa3b, v96
	v_exp_f32_e32 v106, v105
	v_pk_add_f32 v[108:109], v[108:109], 1.0 op_sel_hi:[1,0]
	v_mul_f32_e32 v105, 0xbfb8aa3b, v97
	v_rcp_f32_e32 v114, v109
	v_exp_f32_e32 v104, v104
	v_exp_f32_e32 v105, v105
	v_mul_f32_e32 v107, 0xbfb8aa3b, v93
	v_mul_f32_e32 v99, v99, v114
	v_rcp_f32_e32 v111, v108
	v_pk_add_f32 v[104:105], v[104:105], 1.0 op_sel_hi:[1,0]
	v_exp_f32_e32 v107, v107
	v_mul_f32_e32 v98, v98, v111
	v_rcp_f32_e32 v109, v105
	s_nop 0
	v_mul_f32_e32 v97, v97, v109
	v_rcp_f32_e32 v108, v104
	s_nop 0
	v_mul_f32_e32 v96, v96, v108
	v_mul_f32_e32 v104, 0xbfb8aa3b, v95
	v_exp_f32_e32 v111, v104
	v_pk_add_f32 v[104:105], v[106:107], 1.0 op_sel_hi:[1,0]
	v_pk_add_f32 v[106:107], v[110:111], 1.0 op_sel_hi:[1,0]
	s_nop 0
	v_rcp_f32_e32 v109, v107
	s_nop 0
	v_mul_f32_e32 v95, v95, v109
	v_rcp_f32_e32 v108, v106
	s_nop 0
	v_mul_f32_e32 v94, v94, v108
	v_rcp_f32_e32 v107, v105
	s_nop 0
	v_mul_f32_e32 v93, v93, v107
	v_rcp_f32_e32 v106, v104
	s_nop 0
	v_mul_f32_e32 v92, v92, v106

.LBB0_213:
	s_waitcnt vmcnt(0)
	v_lshlrev_b64 v[100:101], 13, v[176:177]
	v_lshl_add_u64 v[100:101], s[20:21], 0, v[100:101]
	s_mov_b64 s[0:1], 0x100000
	v_pk_mul_f32 v[90:91], v[90:91], v[182:183] op_sel_hi:[1,0]
	v_pk_mul_f32 v[88:89], v[88:89], v[182:183] op_sel_hi:[1,0]
	v_pk_mul_f32 v[86:87], v[86:87], v[182:183] op_sel_hi:[1,0]
	v_pk_mul_f32 v[84:85], v[84:85], v[182:183] op_sel_hi:[1,0]
	v_lshl_add_u64 v[100:101], v[100:101], 0, s[0:1]
	s_and_saveexec_b64 s[0:1], s[10:11]
	s_xor_b64 s[2:3], exec, s[0:1]
	s_cbranch_execz .LBB0_217
	s_cmpk_lt_u32 s29, 0x1000
	s_mov_b64 s[0:1], 0
	s_cbranch_scc1 .LBB0_216
	v_mul_f32_e32 v93, 0xbfb8aa3b, v84
	v_exp_f32_e32 v102, v93
	v_mul_f32_e32 v93, 0xbfb8aa3b, v85
	v_exp_f32_e32 v103, v93
	v_mul_f32_e32 v93, 0xbfb8aa3b, v86
	v_exp_f32_e32 v110, v93
	v_mul_f32_e32 v93, 0xbfb8aa3b, v87
	v_exp_f32_e32 v111, v93
	v_pk_add_f32 v[102:103], v[102:103], 1.0 op_sel_hi:[1,0]
	v_pk_add_f32 v[110:111], v[110:111], 1.0 op_sel_hi:[1,0]
	s_nop 0
	v_rcp_f32_e32 v95, v111
	s_nop 0
	v_mul_f32_e32 v87, v87, v95
	v_rcp_f32_e32 v95, v110
	s_nop 0
	v_mul_f32_e32 v86, v86, v95
	v_rcp_f32_e32 v95, v103
	s_nop 0
	v_mul_f32_e32 v85, v85, v95
	v_rcp_f32_e32 v95, v102
	s_mov_b64 s[0:1], 0x400
	v_mul_f32_e32 v84, v84, v95

.LBB0_217:
	s_andn2_saveexec_b64 s[2:3], s[2:3]
	s_cbranch_execz .LBB0_221
	v_cmp_lt_i32_e32 vcc, s83, v174
	s_and_saveexec_b64 s[42:43], vcc
	s_cbranch_execz .LBB0_220
	v_mul_f32_e32 v93, 0xbfb8aa3b, v88
	v_exp_f32_e32 v102, v93
	v_mul_f32_e32 v93, 0xbfb8aa3b, v84
	v_exp_f32_e32 v110, v93
	v_mul_f32_e32 v93, 0xbfb8aa3b, v89
	v_exp_f32_e32 v103, v93
	v_mul_f32_e32 v93, 0xbfb8aa3b, v85
	v_exp_f32_e32 v111, v93
	v_mul_f32_e32 v93, 0xbfb8aa3b, v90
	v_exp_f32_e32 v112, v93
	v_mul_f32_e32 v93, 0xbfb8aa3b, v86
	v_exp_f32_e32 v114, v93
	v_mul_f32_e32 v93, 0xbfb8aa3b, v91
	v_exp_f32_e32 v113, v93
	v_pk_add_f32 v[102:103], v[102:103], 1.0 op_sel_hi:[1,0]
	v_pk_add_f32 v[112:113], v[112:113], 1.0 op_sel_hi:[1,0]
	s_nop 0
	v_rcp_f32_e32 v95, v113
	s_nop 0
	v_mul_f32_e32 v91, v91, v95
	v_rcp_f32_e32 v95, v112
	s_nop 0
	v_mul_f32_e32 v90, v90, v95
	v_rcp_f32_e32 v95, v103
	s_nop 0
	v_mul_f32_e32 v89, v89, v95
	v_rcp_f32_e32 v95, v102
	s_nop 0
	v_mul_f32_e32 v88, v88, v95
	v_mul_f32_e32 v93, 0xbfb8aa3b, v87
	v_exp_f32_e32 v115, v93
	v_pk_add_f32 v[102:103], v[110:111], 1.0 op_sel_hi:[1,0]
	v_pk_add_f32 v[110:111], v[114:115], 1.0 op_sel_hi:[1,0]
	s_nop 0
	v_rcp_f32_e32 v95, v111
	s_nop 0
	v_mul_f32_e32 v87, v87, v95
	v_rcp_f32_e32 v95, v110
	s_nop 0
	v_mul_f32_e32 v86, v86, v95
	v_rcp_f32_e32 v95, v103
	s_nop 0
	v_mul_f32_e32 v85, v85, v95
	v_rcp_f32_e32 v95, v102
	s_nop 0
	v_mul_f32_e32 v84, v84, v95

.LBB0_221:
	s_or_b64 exec, exec, s[2:3]
	v_mov_b32_e32 v183, v182
	v_mov_b32_e32 v84, v182
	v_mov_b32_e32 v85, v182
	v_pk_mul_f32 v[82:83], v[82:83], v[84:85]
	v_pk_mul_f32 v[80:81], v[80:81], v[182:183]
	v_pk_mul_f32 v[78:79], v[78:79], v[84:85]
	v_pk_mul_f32 v[76:77], v[76:77], v[182:183]
	s_and_saveexec_b64 s[0:1], s[8:9]
	s_xor_b64 s[2:3], exec, s[0:1]
	s_cbranch_execz .LBB0_225
	s_cmpk_lt_u32 s29, 0x1000
	s_mov_b64 s[0:1], 0
	s_cbranch_scc1 .LBB0_224
	v_mul_f32_e32 v86, 0xbfb8aa3b, v78
	v_mul_f32_e32 v87, 0xbfb8aa3b, v79
	v_exp_f32_e32 v86, v86
	v_exp_f32_e32 v87, v87
	v_mul_f32_e32 v84, 0xbfb8aa3b, v76
	v_mul_f32_e32 v85, 0xbfb8aa3b, v77
	v_exp_f32_e32 v84, v84
	v_pk_add_f32 v[86:87], v[86:87], 1.0 op_sel_hi:[1,0]
	v_exp_f32_e32 v85, v85
	v_rcp_f32_e32 v89, v87
	v_pk_add_f32 v[84:85], v[84:85], 1.0 op_sel_hi:[1,0]
	v_mul_f32_e32 v79, v79, v89
	v_rcp_f32_e32 v88, v86
	s_nop 0
	v_mul_f32_e32 v78, v78, v88
	v_rcp_f32_e32 v87, v85
	s_nop 0
	v_mul_f32_e32 v77, v77, v87
	v_rcp_f32_e32 v86, v84
	s_mov_b64 s[0:1], 0x400
	v_mul_f32_e32 v76, v76, v86

.LBB0_225:
	s_andn2_saveexec_b64 s[2:3], s[2:3]
	s_cbranch_execz .LBB0_229
	v_cmp_lt_i32_e32 vcc, s83, v152
	s_and_saveexec_b64 s[42:43], vcc
	s_cbranch_execz .LBB0_228
	v_mul_f32_e32 v89, 0xbfb8aa3b, v78
	v_mul_f32_e32 v88, 0xbfb8aa3b, v82
	v_exp_f32_e32 v90, v89
	v_mul_f32_e32 v89, 0xbfb8aa3b, v83
	v_exp_f32_e32 v88, v88
	v_exp_f32_e32 v89, v89
	v_mul_f32_e32 v85, 0xbfb8aa3b, v76
	v_mul_f32_e32 v84, 0xbfb8aa3b, v80
	v_exp_f32_e32 v86, v85
	v_pk_add_f32 v[88:89], v[88:89], 1.0 op_sel_hi:[1,0]
	v_mul_f32_e32 v85, 0xbfb8aa3b, v81
	v_rcp_f32_e32 v93, v89
	v_exp_f32_e32 v84, v84
	v_exp_f32_e32 v85, v85
	v_mul_f32_e32 v87, 0xbfb8aa3b, v77
	v_mul_f32_e32 v83, v83, v93
	v_rcp_f32_e32 v91, v88
	v_pk_add_f32 v[84:85], v[84:85], 1.0 op_sel_hi:[1,0]
	v_exp_f32_e32 v87, v87
	v_mul_f32_e32 v82, v82, v91
	v_rcp_f32_e32 v89, v85
	s_nop 0
	v_mul_f32_e32 v81, v81, v89
	v_rcp_f32_e32 v88, v84
	s_nop 0
	v_mul_f32_e32 v80, v80, v88
	v_mul_f32_e32 v84, 0xbfb8aa3b, v79
	v_exp_f32_e32 v91, v84
	v_pk_add_f32 v[84:85], v[86:87], 1.0 op_sel_hi:[1,0]
	v_pk_add_f32 v[86:87], v[90:91], 1.0 op_sel_hi:[1,0]
	s_nop 0
	v_rcp_f32_e32 v89, v87
	s_nop 0
	v_mul_f32_e32 v79, v79, v89
	v_rcp_f32_e32 v88, v86
	s_nop 0
	v_mul_f32_e32 v78, v78, v88
	v_rcp_f32_e32 v87, v85
	s_nop 0
	v_mul_f32_e32 v77, v77, v87
	v_rcp_f32_e32 v86, v84
	s_nop 0
	v_mul_f32_e32 v76, v76, v86

.LBB0_229:
	s_or_b64 exec, exec, s[2:3]
	v_lshlrev_b64 v[76:77], 13, v[176:177]
	v_lshl_add_u64 v[76:77], s[20:21], 0, v[76:77]
	s_mov_b64 s[0:1], 0x120000
	v_pk_mul_f32 v[74:75], v[74:75], v[180:181] op_sel_hi:[1,0]
	v_pk_mul_f32 v[72:73], v[72:73], v[180:181] op_sel_hi:[1,0]
	v_pk_mul_f32 v[70:71], v[70:71], v[180:181] op_sel_hi:[1,0]
	v_pk_mul_f32 v[68:69], v[68:69], v[180:181] op_sel_hi:[1,0]
	v_lshl_add_u64 v[76:77], v[76:77], 0, s[0:1]
	s_and_saveexec_b64 s[0:1], s[10:11]
	s_xor_b64 s[2:3], exec, s[0:1]
	s_cbranch_execz .LBB0_233
	s_cmpk_lt_u32 s29, 0x1000
	s_mov_b64 s[0:1], 0
	s_cbranch_scc1 .LBB0_232
	v_mul_f32_e32 v80, 0xbfb8aa3b, v70
	v_mul_f32_e32 v81, 0xbfb8aa3b, v71
	v_exp_f32_e32 v80, v80
	v_exp_f32_e32 v81, v81
	v_mul_f32_e32 v78, 0xbfb8aa3b, v68
	v_mul_f32_e32 v79, 0xbfb8aa3b, v69
	v_exp_f32_e32 v78, v78
	v_pk_add_f32 v[80:81], v[80:81], 1.0 op_sel_hi:[1,0]
	v_exp_f32_e32 v79, v79
	v_rcp_f32_e32 v83, v81
	v_pk_add_f32 v[78:79], v[78:79], 1.0 op_sel_hi:[1,0]
	v_mul_f32_e32 v71, v71, v83
	v_rcp_f32_e32 v82, v80
	s_nop 0
	v_mul_f32_e32 v70, v70, v82
	v_rcp_f32_e32 v81, v79
	s_nop 0
	v_mul_f32_e32 v69, v69, v81
	v_rcp_f32_e32 v80, v78
	s_mov_b64 s[0:1], 0x400
	v_mul_f32_e32 v68, v68, v80

.LBB0_233:
	s_andn2_saveexec_b64 s[2:3], s[2:3]
	s_cbranch_execz .LBB0_237
	v_cmp_lt_i32_e32 vcc, s83, v174
	s_and_saveexec_b64 s[42:43], vcc
	s_cbranch_execz .LBB0_236
	v_mul_f32_e32 v83, 0xbfb8aa3b, v70
	v_mul_f32_e32 v82, 0xbfb8aa3b, v74
	v_exp_f32_e32 v84, v83
	v_mul_f32_e32 v83, 0xbfb8aa3b, v75
	v_exp_f32_e32 v82, v82
	v_exp_f32_e32 v83, v83
	v_mul_f32_e32 v79, 0xbfb8aa3b, v68
	v_mul_f32_e32 v78, 0xbfb8aa3b, v72
	v_exp_f32_e32 v80, v79
	v_pk_add_f32 v[82:83], v[82:83], 1.0 op_sel_hi:[1,0]
	v_mul_f32_e32 v79, 0xbfb8aa3b, v73
	v_rcp_f32_e32 v86, v83
	v_exp_f32_e32 v78, v78
	v_exp_f32_e32 v79, v79
	v_mul_f32_e32 v81, 0xbfb8aa3b, v69
	v_mul_f32_e32 v75, v75, v86
	v_rcp_f32_e32 v85, v82
	v_pk_add_f32 v[78:79], v[78:79], 1.0 op_sel_hi:[1,0]
	v_exp_f32_e32 v81, v81
	v_mul_f32_e32 v74, v74, v85
	v_rcp_f32_e32 v83, v79
	s_nop 0
	v_mul_f32_e32 v73, v73, v83
	v_rcp_f32_e32 v82, v78
	s_nop 0
	v_mul_f32_e32 v72, v72, v82
	v_mul_f32_e32 v78, 0xbfb8aa3b, v71
	v_exp_f32_e32 v85, v78
	v_pk_add_f32 v[78:79], v[80:81], 1.0 op_sel_hi:[1,0]
	v_pk_add_f32 v[80:81], v[84:85], 1.0 op_sel_hi:[1,0]
	s_nop 0
	v_rcp_f32_e32 v83, v81
	s_nop 0
	v_mul_f32_e32 v71, v71, v83
	v_rcp_f32_e32 v82, v80
	s_nop 0
	v_mul_f32_e32 v70, v70, v82
	v_rcp_f32_e32 v81, v79
	s_nop 0
	v_mul_f32_e32 v69, v69, v81
	v_rcp_f32_e32 v80, v78
	s_nop 0
	v_mul_f32_e32 v68, v68, v80

.LBB0_237:
	s_or_b64 exec, exec, s[2:3]
	v_mov_b32_e32 v181, v180
	v_mov_b32_e32 v68, v180
	v_mov_b32_e32 v69, v180
	v_pk_mul_f32 v[66:67], v[66:67], v[68:69]
	v_pk_mul_f32 v[64:65], v[64:65], v[180:181]
	v_pk_mul_f32 v[62:63], v[62:63], v[68:69]
	v_pk_mul_f32 v[60:61], v[60:61], v[180:181]
	s_and_saveexec_b64 s[0:1], s[8:9]
	s_xor_b64 s[2:3], exec, s[0:1]
	s_cbranch_execz .LBB0_241
	s_cmpk_lt_u32 s29, 0x1000
	s_mov_b64 s[0:1], 0
	s_cbranch_scc1 .LBB0_240
	v_mul_f32_e32 v70, 0xbfb8aa3b, v62
	v_mul_f32_e32 v71, 0xbfb8aa3b, v63
	v_exp_f32_e32 v70, v70
	v_exp_f32_e32 v71, v71
	v_mul_f32_e32 v68, 0xbfb8aa3b, v60
	v_mul_f32_e32 v69, 0xbfb8aa3b, v61
	v_exp_f32_e32 v68, v68
	v_pk_add_f32 v[70:71], v[70:71], 1.0 op_sel_hi:[1,0]
	v_exp_f32_e32 v69, v69
	v_rcp_f32_e32 v73, v71
	v_pk_add_f32 v[68:69], v[68:69], 1.0 op_sel_hi:[1,0]
	v_mul_f32_e32 v63, v63, v73
	v_rcp_f32_e32 v72, v70
	s_nop 0
	v_mul_f32_e32 v62, v62, v72
	v_rcp_f32_e32 v71, v69
	s_nop 0
	v_mul_f32_e32 v61, v61, v71
	v_rcp_f32_e32 v70, v68
	s_mov_b64 s[0:1], 0x400
	v_mul_f32_e32 v60, v60, v70

.LBB0_241:
	s_andn2_saveexec_b64 s[2:3], s[2:3]
	s_cbranch_execz .LBB0_245
	v_cmp_lt_i32_e32 vcc, s83, v152
	s_and_saveexec_b64 s[42:43], vcc
	s_cbranch_execz .LBB0_244
	v_mul_f32_e32 v73, 0xbfb8aa3b, v62
	v_mul_f32_e32 v72, 0xbfb8aa3b, v66
	v_exp_f32_e32 v74, v73
	v_mul_f32_e32 v73, 0xbfb8aa3b, v67
	v_exp_f32_e32 v72, v72
	v_exp_f32_e32 v73, v73
	v_mul_f32_e32 v69, 0xbfb8aa3b, v60
	v_mul_f32_e32 v68, 0xbfb8aa3b, v64
	v_exp_f32_e32 v70, v69
	v_pk_add_f32 v[72:73], v[72:73], 1.0 op_sel_hi:[1,0]
	v_mul_f32_e32 v69, 0xbfb8aa3b, v65
	v_rcp_f32_e32 v78, v73
	v_exp_f32_e32 v68, v68
	v_exp_f32_e32 v69, v69
	v_mul_f32_e32 v71, 0xbfb8aa3b, v61
	v_mul_f32_e32 v67, v67, v78
	v_rcp_f32_e32 v75, v72
	v_pk_add_f32 v[68:69], v[68:69], 1.0 op_sel_hi:[1,0]
	v_exp_f32_e32 v71, v71
	v_mul_f32_e32 v66, v66, v75
	v_rcp_f32_e32 v73, v69
	s_nop 0
	v_mul_f32_e32 v65, v65, v73
	v_rcp_f32_e32 v72, v68
	s_nop 0
	v_mul_f32_e32 v64, v64, v72
	v_mul_f32_e32 v68, 0xbfb8aa3b, v63
	v_exp_f32_e32 v75, v68
	v_pk_add_f32 v[68:69], v[70:71], 1.0 op_sel_hi:[1,0]
	v_pk_add_f32 v[70:71], v[74:75], 1.0 op_sel_hi:[1,0]
	s_nop 0
	v_rcp_f32_e32 v73, v71
	s_nop 0
	v_mul_f32_e32 v63, v63, v73
	v_rcp_f32_e32 v72, v70
	s_nop 0
	v_mul_f32_e32 v62, v62, v72
	v_rcp_f32_e32 v71, v69
	s_nop 0
	v_mul_f32_e32 v61, v61, v71
	v_rcp_f32_e32 v70, v68
	s_nop 0
	v_mul_f32_e32 v60, v60, v70

.LBB0_245:
	s_or_b64 exec, exec, s[2:3]
	v_lshlrev_b64 v[60:61], 13, v[176:177]
	v_lshl_add_u64 v[60:61], s[20:21], 0, v[60:61]
	s_mov_b64 s[0:1], 0x140000
	v_pk_mul_f32 v[58:59], v[58:59], v[178:179] op_sel_hi:[1,0]
	v_pk_mul_f32 v[56:57], v[56:57], v[178:179] op_sel_hi:[1,0]
	v_pk_mul_f32 v[54:55], v[54:55], v[178:179] op_sel_hi:[1,0]
	v_pk_mul_f32 v[52:53], v[52:53], v[178:179] op_sel_hi:[1,0]
	v_lshl_add_u64 v[60:61], v[60:61], 0, s[0:1]
	s_and_saveexec_b64 s[0:1], s[10:11]
	s_xor_b64 s[2:3], exec, s[0:1]
	s_cbranch_execz .LBB0_249
	s_cmpk_lt_u32 s29, 0x1000
	s_mov_b64 s[0:1], 0
	s_cbranch_scc1 .LBB0_248
	v_mul_f32_e32 v64, 0xbfb8aa3b, v54
	v_mul_f32_e32 v65, 0xbfb8aa3b, v55
	v_exp_f32_e32 v64, v64
	v_exp_f32_e32 v65, v65
	v_mul_f32_e32 v62, 0xbfb8aa3b, v52
	v_mul_f32_e32 v63, 0xbfb8aa3b, v53
	v_exp_f32_e32 v62, v62
	v_pk_add_f32 v[64:65], v[64:65], 1.0 op_sel_hi:[1,0]
	v_exp_f32_e32 v63, v63
	v_rcp_f32_e32 v67, v65
	v_pk_add_f32 v[62:63], v[62:63], 1.0 op_sel_hi:[1,0]
	v_mul_f32_e32 v55, v55, v67
	v_rcp_f32_e32 v66, v64
	s_nop 0
	v_mul_f32_e32 v54, v54, v66
	v_rcp_f32_e32 v65, v63
	s_nop 0
	v_mul_f32_e32 v53, v53, v65
	v_rcp_f32_e32 v64, v62
	s_mov_b64 s[0:1], 0x400
	v_mul_f32_e32 v52, v52, v64

.LBB0_249:
	s_andn2_saveexec_b64 s[2:3], s[2:3]
	s_cbranch_execz .LBB0_253
	v_cmp_lt_i32_e32 vcc, s83, v174
	s_and_saveexec_b64 s[42:43], vcc
	s_cbranch_execz .LBB0_252
	v_mul_f32_e32 v67, 0xbfb8aa3b, v54
	v_mul_f32_e32 v66, 0xbfb8aa3b, v58
	v_exp_f32_e32 v68, v67
	v_mul_f32_e32 v67, 0xbfb8aa3b, v59
	v_exp_f32_e32 v66, v66
	v_exp_f32_e32 v67, v67
	v_mul_f32_e32 v63, 0xbfb8aa3b, v52
	v_mul_f32_e32 v62, 0xbfb8aa3b, v56
	v_exp_f32_e32 v64, v63
	v_pk_add_f32 v[66:67], v[66:67], 1.0 op_sel_hi:[1,0]
	v_mul_f32_e32 v63, 0xbfb8aa3b, v57
	v_rcp_f32_e32 v70, v67
	v_exp_f32_e32 v62, v62
	v_exp_f32_e32 v63, v63
	v_mul_f32_e32 v65, 0xbfb8aa3b, v53
	v_mul_f32_e32 v59, v59, v70
	v_rcp_f32_e32 v69, v66
	v_pk_add_f32 v[62:63], v[62:63], 1.0 op_sel_hi:[1,0]
	v_exp_f32_e32 v65, v65
	v_mul_f32_e32 v58, v58, v69
	v_rcp_f32_e32 v67, v63
	s_nop 0
	v_mul_f32_e32 v57, v57, v67
	v_rcp_f32_e32 v66, v62
	s_nop 0
	v_mul_f32_e32 v56, v56, v66
	v_mul_f32_e32 v62, 0xbfb8aa3b, v55
	v_exp_f32_e32 v69, v62
	v_pk_add_f32 v[62:63], v[64:65], 1.0 op_sel_hi:[1,0]
	v_pk_add_f32 v[64:65], v[68:69], 1.0 op_sel_hi:[1,0]
	s_nop 0
	v_rcp_f32_e32 v67, v65
	s_nop 0
	v_mul_f32_e32 v55, v55, v67
	v_rcp_f32_e32 v66, v64
	s_nop 0
	v_mul_f32_e32 v54, v54, v66
	v_rcp_f32_e32 v65, v63
	s_nop 0
	v_mul_f32_e32 v53, v53, v65
	v_rcp_f32_e32 v64, v62
	s_nop 0
	v_mul_f32_e32 v52, v52, v64

.LBB0_253:
	s_or_b64 exec, exec, s[2:3]
	v_mov_b32_e32 v179, v178
	v_mov_b32_e32 v52, v178
	v_mov_b32_e32 v53, v178
	v_pk_mul_f32 v[50:51], v[50:51], v[52:53]
	v_pk_mul_f32 v[48:49], v[48:49], v[178:179]
	v_pk_mul_f32 v[46:47], v[46:47], v[52:53]
	v_pk_mul_f32 v[44:45], v[44:45], v[178:179]
	s_and_saveexec_b64 s[0:1], s[8:9]
	s_xor_b64 s[2:3], exec, s[0:1]
	s_cbranch_execz .LBB0_257
	s_cmpk_lt_u32 s29, 0x1000
	s_mov_b64 s[0:1], 0
	s_cbranch_scc1 .LBB0_256
	v_mul_f32_e32 v54, 0xbfb8aa3b, v46
	v_mul_f32_e32 v55, 0xbfb8aa3b, v47
	v_exp_f32_e32 v54, v54
	v_exp_f32_e32 v55, v55
	v_mul_f32_e32 v52, 0xbfb8aa3b, v44
	v_mul_f32_e32 v53, 0xbfb8aa3b, v45
	v_exp_f32_e32 v52, v52
	v_pk_add_f32 v[54:55], v[54:55], 1.0 op_sel_hi:[1,0]
	v_exp_f32_e32 v53, v53
	v_rcp_f32_e32 v57, v55
	v_pk_add_f32 v[52:53], v[52:53], 1.0 op_sel_hi:[1,0]
	v_mul_f32_e32 v47, v47, v57
	v_rcp_f32_e32 v56, v54
	s_nop 0
	v_mul_f32_e32 v46, v46, v56
	v_rcp_f32_e32 v55, v53
	s_nop 0
	v_mul_f32_e32 v45, v45, v55
	v_rcp_f32_e32 v54, v52
	s_mov_b64 s[0:1], 0x400
	v_mul_f32_e32 v44, v44, v54

.LBB0_257:
	s_andn2_saveexec_b64 s[2:3], s[2:3]
	s_cbranch_execz .LBB0_261
	v_cmp_lt_i32_e32 vcc, s83, v152
	s_and_saveexec_b64 s[42:43], vcc
	s_cbranch_execz .LBB0_260
	v_mul_f32_e32 v57, 0xbfb8aa3b, v46
	v_mul_f32_e32 v56, 0xbfb8aa3b, v50
	v_exp_f32_e32 v58, v57
	v_mul_f32_e32 v57, 0xbfb8aa3b, v51
	v_exp_f32_e32 v56, v56
	v_exp_f32_e32 v57, v57
	v_mul_f32_e32 v53, 0xbfb8aa3b, v44
	v_mul_f32_e32 v52, 0xbfb8aa3b, v48
	v_exp_f32_e32 v54, v53
	v_pk_add_f32 v[56:57], v[56:57], 1.0 op_sel_hi:[1,0]
	v_mul_f32_e32 v53, 0xbfb8aa3b, v49
	v_rcp_f32_e32 v62, v57
	v_exp_f32_e32 v52, v52
	v_exp_f32_e32 v53, v53
	v_mul_f32_e32 v55, 0xbfb8aa3b, v45
	v_mul_f32_e32 v51, v51, v62
	v_rcp_f32_e32 v59, v56
	v_pk_add_f32 v[52:53], v[52:53], 1.0 op_sel_hi:[1,0]
	v_exp_f32_e32 v55, v55
	v_mul_f32_e32 v50, v50, v59
	v_rcp_f32_e32 v57, v53
	s_nop 0
	v_mul_f32_e32 v49, v49, v57
	v_rcp_f32_e32 v56, v52
	s_nop 0
	v_mul_f32_e32 v48, v48, v56
	v_mul_f32_e32 v52, 0xbfb8aa3b, v47
	v_exp_f32_e32 v59, v52
	v_pk_add_f32 v[52:53], v[54:55], 1.0 op_sel_hi:[1,0]
	v_pk_add_f32 v[54:55], v[58:59], 1.0 op_sel_hi:[1,0]
	s_nop 0
	v_rcp_f32_e32 v57, v55
	s_nop 0
	v_mul_f32_e32 v47, v47, v57
	v_rcp_f32_e32 v56, v54
	s_nop 0
	v_mul_f32_e32 v46, v46, v56
	v_rcp_f32_e32 v55, v53
	s_nop 0
	v_mul_f32_e32 v45, v45, v55
	v_rcp_f32_e32 v54, v52
	s_nop 0
	v_mul_f32_e32 v44, v44, v54

.LBB0_261:
	s_or_b64 exec, exec, s[2:3]
	v_lshlrev_b64 v[44:45], 13, v[176:177]
	v_lshl_add_u64 v[44:45], s[20:21], 0, v[44:45]
	s_mov_b64 s[0:1], 0x160000
	v_pk_mul_f32 v[18:19], v[18:19], v[172:173] op_sel_hi:[1,0]
	v_pk_mul_f32 v[16:17], v[16:17], v[172:173] op_sel_hi:[1,0]
	v_pk_mul_f32 v[10:11], v[10:11], v[172:173] op_sel_hi:[1,0]
	v_pk_mul_f32 v[8:9], v[8:9], v[172:173] op_sel_hi:[1,0]
	v_lshl_add_u64 v[44:45], v[44:45], 0, s[0:1]
	s_and_saveexec_b64 s[0:1], s[10:11]
	s_xor_b64 s[2:3], exec, s[0:1]
	s_cbranch_execz .LBB0_265
	s_cmpk_lt_u32 s29, 0x1000
	s_mov_b64 s[0:1], 0
	s_cbranch_scc1 .LBB0_264
	v_mul_f32_e32 v48, 0xbfb8aa3b, v10
	v_mul_f32_e32 v49, 0xbfb8aa3b, v11
	v_exp_f32_e32 v48, v48
	v_exp_f32_e32 v49, v49
	v_mul_f32_e32 v46, 0xbfb8aa3b, v8
	v_mul_f32_e32 v47, 0xbfb8aa3b, v9
	v_exp_f32_e32 v46, v46
	v_pk_add_f32 v[48:49], v[48:49], 1.0 op_sel_hi:[1,0]
	v_exp_f32_e32 v47, v47
	v_rcp_f32_e32 v51, v49
	v_pk_add_f32 v[46:47], v[46:47], 1.0 op_sel_hi:[1,0]
	v_mul_f32_e32 v11, v11, v51
	v_rcp_f32_e32 v50, v48
	s_nop 0
	v_mul_f32_e32 v10, v10, v50
	v_rcp_f32_e32 v49, v47
	s_nop 0
	v_mul_f32_e32 v9, v9, v49
	v_rcp_f32_e32 v48, v46
	s_mov_b64 s[0:1], 0x400
	v_mul_f32_e32 v8, v8, v48

.LBB0_265:
	s_andn2_saveexec_b64 s[2:3], s[2:3]
	s_cbranch_execz .LBB0_269
	v_cmp_lt_i32_e32 vcc, s83, v174
	s_and_saveexec_b64 s[10:11], vcc
	s_cbranch_execz .LBB0_268
	v_mul_f32_e32 v51, 0xbfb8aa3b, v10
	v_mul_f32_e32 v50, 0xbfb8aa3b, v18
	v_exp_f32_e32 v52, v51
	v_mul_f32_e32 v51, 0xbfb8aa3b, v19
	v_exp_f32_e32 v50, v50
	v_exp_f32_e32 v51, v51
	v_mul_f32_e32 v47, 0xbfb8aa3b, v8
	v_mul_f32_e32 v46, 0xbfb8aa3b, v16
	v_exp_f32_e32 v48, v47
	v_pk_add_f32 v[50:51], v[50:51], 1.0 op_sel_hi:[1,0]
	v_mul_f32_e32 v47, 0xbfb8aa3b, v17
	v_rcp_f32_e32 v54, v51
	v_exp_f32_e32 v46, v46
	v_exp_f32_e32 v47, v47
	v_mul_f32_e32 v49, 0xbfb8aa3b, v9
	v_mul_f32_e32 v19, v19, v54
	v_rcp_f32_e32 v53, v50
	v_pk_add_f32 v[46:47], v[46:47], 1.0 op_sel_hi:[1,0]
	v_exp_f32_e32 v49, v49
	v_mul_f32_e32 v18, v18, v53
	v_rcp_f32_e32 v51, v47
	s_nop 0
	v_mul_f32_e32 v17, v17, v51
	v_rcp_f32_e32 v50, v46
	s_nop 0
	v_mul_f32_e32 v16, v16, v50
	v_mul_f32_e32 v46, 0xbfb8aa3b, v11
	v_exp_f32_e32 v53, v46
	v_pk_add_f32 v[46:47], v[48:49], 1.0 op_sel_hi:[1,0]
	v_pk_add_f32 v[48:49], v[52:53], 1.0 op_sel_hi:[1,0]
	s_nop 0
	v_rcp_f32_e32 v51, v49
	s_nop 0
	v_mul_f32_e32 v11, v11, v51
	v_rcp_f32_e32 v50, v48
	s_nop 0
	v_mul_f32_e32 v10, v10, v50
	v_rcp_f32_e32 v49, v47
	s_nop 0
	v_mul_f32_e32 v9, v9, v49
	v_rcp_f32_e32 v48, v46
	s_nop 0
	v_mul_f32_e32 v8, v8, v48

.LBB0_269:
	s_or_b64 exec, exec, s[2:3]
	v_mov_b32_e32 v173, v172
	v_mov_b32_e32 v8, v172
	v_mov_b32_e32 v9, v172
	v_pk_mul_f32 v[6:7], v[6:7], v[8:9]
	v_pk_mul_f32 v[4:5], v[4:5], v[172:173]
	v_pk_mul_f32 v[2:3], v[2:3], v[8:9]
	v_pk_mul_f32 v[0:1], v[0:1], v[172:173]
	s_and_saveexec_b64 s[0:1], s[8:9]
	s_xor_b64 s[2:3], exec, s[0:1]
	s_cbranch_execz .LBB0_273
	s_cmpk_lt_u32 s29, 0x1000
	s_mov_b64 s[0:1], 0
	s_cbranch_scc1 .LBB0_272
	v_mul_f32_e32 v10, 0xbfb8aa3b, v2
	v_mul_f32_e32 v11, 0xbfb8aa3b, v3
	v_exp_f32_e32 v10, v10
	v_exp_f32_e32 v11, v11
	v_mul_f32_e32 v8, 0xbfb8aa3b, v0
	v_mul_f32_e32 v9, 0xbfb8aa3b, v1
	v_exp_f32_e32 v8, v8
	v_pk_add_f32 v[10:11], v[10:11], 1.0 op_sel_hi:[1,0]
	v_exp_f32_e32 v9, v9
	v_rcp_f32_e32 v17, v11
	v_pk_add_f32 v[8:9], v[8:9], 1.0 op_sel_hi:[1,0]
	v_mul_f32_e32 v3, v3, v17
	v_rcp_f32_e32 v16, v10
	s_nop 0
	v_mul_f32_e32 v2, v2, v16
	v_rcp_f32_e32 v11, v9
	s_nop 0
	v_mul_f32_e32 v1, v1, v11
	v_rcp_f32_e32 v10, v8
	s_mov_b64 s[0:1], 0x400
	v_mul_f32_e32 v0, v0, v10

.LBB0_273:
	s_andn2_saveexec_b64 s[2:3], s[2:3]
	s_cbranch_execz .LBB0_277
	v_cmp_lt_i32_e32 vcc, s83, v152
	s_and_saveexec_b64 s[8:9], vcc
	s_cbranch_execz .LBB0_276
	v_mul_f32_e32 v17, 0xbfb8aa3b, v2
	v_mul_f32_e32 v16, 0xbfb8aa3b, v6
	v_exp_f32_e32 v18, v17
	v_mul_f32_e32 v17, 0xbfb8aa3b, v7
	v_exp_f32_e32 v16, v16
	v_exp_f32_e32 v17, v17
	v_mul_f32_e32 v9, 0xbfb8aa3b, v0
	v_mul_f32_e32 v8, 0xbfb8aa3b, v4
	v_exp_f32_e32 v10, v9
	v_pk_add_f32 v[16:17], v[16:17], 1.0 op_sel_hi:[1,0]
	v_mul_f32_e32 v9, 0xbfb8aa3b, v5
	v_rcp_f32_e32 v46, v17
	v_exp_f32_e32 v8, v8
	v_exp_f32_e32 v9, v9
	v_mul_f32_e32 v11, 0xbfb8aa3b, v1
	v_mul_f32_e32 v7, v7, v46
	v_rcp_f32_e32 v19, v16
	v_pk_add_f32 v[8:9], v[8:9], 1.0 op_sel_hi:[1,0]
	v_exp_f32_e32 v11, v11
	v_mul_f32_e32 v6, v6, v19
	v_rcp_f32_e32 v17, v9
	s_nop 0
	v_mul_f32_e32 v5, v5, v17
	v_rcp_f32_e32 v16, v8
	s_nop 0
	v_mul_f32_e32 v4, v4, v16
	v_mul_f32_e32 v8, 0xbfb8aa3b, v3
	v_exp_f32_e32 v19, v8
	v_pk_add_f32 v[8:9], v[10:11], 1.0 op_sel_hi:[1,0]
	v_pk_add_f32 v[10:11], v[18:19], 1.0 op_sel_hi:[1,0]
	s_nop 0
	v_rcp_f32_e32 v17, v11
	s_nop 0
	v_mul_f32_e32 v3, v3, v17
	v_rcp_f32_e32 v16, v10
	s_nop 0
	v_mul_f32_e32 v2, v2, v16
	v_rcp_f32_e32 v11, v9
	s_nop 0
	v_mul_f32_e32 v1, v1, v11
	v_rcp_f32_e32 v10, v8
	s_nop 0
	v_mul_f32_e32 v0, v0, v10

.LBB0_682:
	s_cmp_eq_u32 s2, 3
	s_cselect_b64 s[54:55], -1, 0
	s_cmp_lg_u32 s2, 3
	s_cselect_b64 s[20:21], -1, 0
	s_cmpk_lt_u32 s3, 0x800
	s_mov_b32 s0, 0x3e0293ee
	v_pk_mul_f32 v[226:227], v[160:161], s[0:1] op_sel_hi:[1,0]
	v_pk_mul_f32 v[234:235], v[158:159], s[0:1] op_sel_hi:[1,0]
	v_pk_mul_f32 v[152:153], v[156:157], s[0:1] op_sel_hi:[1,0]
	v_pk_mul_f32 v[236:237], v[154:155], s[0:1] op_sel_hi:[1,0]
	s_cselect_b64 s[10:11], -1, 0
	v_cndmask_b32_e64 v155, v155, v237, s[10:11]
	v_cndmask_b32_e64 v154, v154, v236, s[10:11]
	v_cndmask_b32_e64 v153, v157, v153, s[10:11]
	v_cndmask_b32_e64 v152, v156, v152, s[10:11]
	v_cndmask_b32_e64 v159, v159, v235, s[10:11]
	v_cndmask_b32_e64 v158, v158, v234, s[10:11]
	v_cndmask_b32_e64 v157, v161, v227, s[10:11]
	v_cndmask_b32_e64 v156, v160, v226, s[10:11]
	s_and_b64 vcc, exec, s[20:21]
	s_cbranch_vccnz .LBB0_684
	v_mul_f32_e32 v181, 0xbfb8aa3b, v155
	v_exp_f32_e32 v227, v181
	v_mul_f32_e32 v181, 0xbfb8aa3b, v156
	v_exp_f32_e32 v234, v181
	v_mul_f32_e32 v181, 0xbfb8aa3b, v152
	v_exp_f32_e32 v236, v181
	v_mul_f32_e32 v181, 0xbfb8aa3b, v157
	v_exp_f32_e32 v235, v181
	v_mul_f32_e32 v161, 0xbfb8aa3b, v154
	v_mul_f32_e32 v160, 0xbfb8aa3b, v158
	v_exp_f32_e32 v226, v161
	v_pk_add_f32 v[234:235], v[234:235], 1.0 op_sel_hi:[1,0]
	v_mul_f32_e32 v161, 0xbfb8aa3b, v159
	v_rcp_f32_e32 v183, v235
	v_exp_f32_e32 v160, v160
	v_exp_f32_e32 v161, v161
	v_mul_f32_e32 v157, v157, v183
	v_rcp_f32_e32 v183, v234
	v_pk_add_f32 v[160:161], v[160:161], 1.0 op_sel_hi:[1,0]
	v_mul_f32_e32 v156, v156, v183
	v_rcp_f32_e32 v183, v161
	s_nop 0
	v_mul_f32_e32 v159, v159, v183
	v_rcp_f32_e32 v181, v160
	s_nop 0
	v_mul_f32_e32 v158, v158, v181
	v_mul_f32_e32 v160, 0xbfb8aa3b, v153
	v_exp_f32_e32 v237, v160
	v_pk_add_f32 v[160:161], v[226:227], 1.0 op_sel_hi:[1,0]
	v_pk_add_f32 v[226:227], v[236:237], 1.0 op_sel_hi:[1,0]
	s_nop 0
	v_rcp_f32_e32 v183, v227
	s_nop 0
	v_mul_f32_e32 v153, v153, v183
	v_rcp_f32_e32 v183, v226
	s_nop 0
	v_mul_f32_e32 v152, v152, v183
	v_rcp_f32_e32 v183, v161
	s_nop 0
	v_mul_f32_e32 v155, v155, v183
	v_rcp_f32_e32 v181, v160
	s_nop 0
	v_mul_f32_e32 v154, v154, v181

.LBB0_700:
	s_mov_b32 s0, 0x3e0293ee
	v_pk_mul_f32 v[158:159], v[152:153], s[0:1] op_sel_hi:[1,0]
	v_pk_mul_f32 v[144:145], v[148:149], s[0:1] op_sel_hi:[1,0]
	v_pk_mul_f32 v[160:161], v[150:151], s[0:1] op_sel_hi:[1,0]
	v_pk_mul_f32 v[220:221], v[146:147], s[0:1] op_sel_hi:[1,0]
	v_cndmask_b32_e64 v144, v148, v144, s[10:11]
	v_cndmask_b32_e64 v148, v152, v158, s[10:11]
	v_cndmask_b32_e64 v152, 0, 1, s[54:55]
	v_cndmask_b32_e64 v145, v149, v145, s[10:11]
	v_cndmask_b32_e64 v147, v147, v221, s[10:11]
	v_cndmask_b32_e64 v146, v146, v220, s[10:11]
	v_cndmask_b32_e64 v149, v153, v159, s[10:11]
	v_cndmask_b32_e64 v151, v151, v161, s[10:11]
	v_cmp_ne_u32_e64 s[12:13], 1, v152
	s_andn2_b64 vcc, exec, s[54:55]
	v_cndmask_b32_e64 v150, v150, v160, s[10:11]
	s_cbranch_vccnz .LBB0_702
	v_mul_f32_e32 v155, 0xbfb8aa3b, v147
	v_exp_f32_e32 v159, v155
	v_mul_f32_e32 v155, 0xbfb8aa3b, v148
	v_exp_f32_e32 v160, v155
	v_mul_f32_e32 v155, 0xbfb8aa3b, v144
	v_exp_f32_e32 v220, v155
	v_mul_f32_e32 v155, 0xbfb8aa3b, v149
	v_exp_f32_e32 v161, v155
	v_mul_f32_e32 v153, 0xbfb8aa3b, v146
	v_mul_f32_e32 v152, 0xbfb8aa3b, v150
	v_exp_f32_e32 v158, v153
	v_pk_add_f32 v[160:161], v[160:161], 1.0 op_sel_hi:[1,0]
	v_mul_f32_e32 v153, 0xbfb8aa3b, v151
	v_rcp_f32_e32 v177, v161
	v_exp_f32_e32 v152, v152
	v_exp_f32_e32 v153, v153
	v_mul_f32_e32 v149, v149, v177
	v_rcp_f32_e32 v161, v160
	v_pk_add_f32 v[152:153], v[152:153], 1.0 op_sel_hi:[1,0]
	v_mul_f32_e32 v148, v148, v161
	v_rcp_f32_e32 v160, v153
	s_nop 0
	v_mul_f32_e32 v151, v151, v160
	v_rcp_f32_e32 v155, v152
	s_nop 0
	v_mul_f32_e32 v150, v150, v155
	v_mul_f32_e32 v152, 0xbfb8aa3b, v145
	v_exp_f32_e32 v221, v152
	v_pk_add_f32 v[152:153], v[158:159], 1.0 op_sel_hi:[1,0]
	v_pk_add_f32 v[158:159], v[220:221], 1.0 op_sel_hi:[1,0]
	s_nop 0
	v_rcp_f32_e32 v160, v159
	s_nop 0
	v_mul_f32_e32 v145, v145, v160
	v_rcp_f32_e32 v159, v158
	s_nop 0
	v_mul_f32_e32 v144, v144, v159
	v_rcp_f32_e32 v158, v153
	s_nop 0
	v_mul_f32_e32 v147, v147, v158
	v_rcp_f32_e32 v155, v152
	s_nop 0
	v_mul_f32_e32 v146, v146, v155

.LBB0_712:
	s_mov_b32 s0, 0x3e0293ee
	v_pk_mul_f32 v[150:151], v[144:145], s[0:1] op_sel_hi:[1,0]
	v_pk_mul_f32 v[152:153], v[142:143], s[0:1] op_sel_hi:[1,0]
	v_pk_mul_f32 v[136:137], v[140:141], s[0:1] op_sel_hi:[1,0]
	v_pk_mul_f32 v[156:157], v[138:139], s[0:1] op_sel_hi:[1,0]
	v_cndmask_b32_e64 v137, v141, v137, s[10:11]
	v_cndmask_b32_e64 v136, v140, v136, s[10:11]
	v_cndmask_b32_e64 v139, v139, v157, s[10:11]
	v_cndmask_b32_e64 v138, v138, v156, s[10:11]
	v_cndmask_b32_e64 v141, v145, v151, s[10:11]
	v_cndmask_b32_e64 v140, v144, v150, s[10:11]
	v_cndmask_b32_e64 v143, v143, v153, s[10:11]
	s_and_b64 vcc, exec, s[12:13]
	v_cndmask_b32_e64 v142, v142, v152, s[10:11]
	s_cbranch_vccnz .LBB0_714
	v_mul_f32_e32 v153, 0xbfb8aa3b, v136
	v_mul_f32_e32 v152, 0xbfb8aa3b, v140
	v_exp_f32_e32 v156, v153
	v_mul_f32_e32 v153, 0xbfb8aa3b, v141
	v_exp_f32_e32 v152, v152
	v_exp_f32_e32 v153, v153
	v_mul_f32_e32 v145, 0xbfb8aa3b, v138
	v_mul_f32_e32 v144, 0xbfb8aa3b, v142
	v_exp_f32_e32 v150, v145
	v_pk_add_f32 v[152:153], v[152:153], 1.0 op_sel_hi:[1,0]
	v_mul_f32_e32 v145, 0xbfb8aa3b, v143
	v_rcp_f32_e32 v157, v153
	v_exp_f32_e32 v144, v144
	v_exp_f32_e32 v145, v145
	v_mul_f32_e32 v151, 0xbfb8aa3b, v139
	v_mul_f32_e32 v141, v141, v157
	v_rcp_f32_e32 v155, v152
	v_pk_add_f32 v[144:145], v[144:145], 1.0 op_sel_hi:[1,0]
	v_exp_f32_e32 v151, v151
	v_mul_f32_e32 v140, v140, v155
	v_rcp_f32_e32 v153, v145
	s_nop 0
	v_mul_f32_e32 v143, v143, v153
	v_rcp_f32_e32 v152, v144
	s_nop 0
	v_mul_f32_e32 v142, v142, v152
	v_mul_f32_e32 v144, 0xbfb8aa3b, v137
	v_exp_f32_e32 v157, v144
	v_pk_add_f32 v[144:145], v[150:151], 1.0 op_sel_hi:[1,0]
	v_pk_add_f32 v[150:151], v[156:157], 1.0 op_sel_hi:[1,0]
	s_nop 0
	v_rcp_f32_e32 v153, v151
	s_nop 0
	v_mul_f32_e32 v137, v137, v153
	v_rcp_f32_e32 v152, v150
	s_nop 0
	v_mul_f32_e32 v136, v136, v152
	v_rcp_f32_e32 v151, v145
	s_nop 0
	v_mul_f32_e32 v139, v139, v151
	v_rcp_f32_e32 v150, v144
	s_nop 0
	v_mul_f32_e32 v138, v138, v150

.LBB0_724:
	s_mov_b32 s0, 0x3e0293ee
	v_pk_mul_f32 v[140:141], v[136:137], s[0:1] op_sel_hi:[1,0]
	v_pk_mul_f32 v[142:143], v[134:135], s[0:1] op_sel_hi:[1,0]
	v_pk_mul_f32 v[128:129], v[132:133], s[0:1] op_sel_hi:[1,0]
	v_pk_mul_f32 v[144:145], v[130:131], s[0:1] op_sel_hi:[1,0]
	v_cndmask_b32_e64 v129, v133, v129, s[10:11]
	v_cndmask_b32_e64 v128, v132, v128, s[10:11]
	v_cndmask_b32_e64 v131, v131, v145, s[10:11]
	v_cndmask_b32_e64 v130, v130, v144, s[10:11]
	v_cndmask_b32_e64 v133, v137, v141, s[10:11]
	v_cndmask_b32_e64 v132, v136, v140, s[10:11]
	v_cndmask_b32_e64 v135, v135, v143, s[10:11]
	s_and_b64 vcc, exec, s[12:13]
	v_cndmask_b32_e64 v134, v134, v142, s[10:11]
	s_cbranch_vccnz .LBB0_726
	v_mul_f32_e32 v143, 0xbfb8aa3b, v128
	v_mul_f32_e32 v142, 0xbfb8aa3b, v132
	v_exp_f32_e32 v144, v143
	v_mul_f32_e32 v143, 0xbfb8aa3b, v133
	v_exp_f32_e32 v142, v142
	v_exp_f32_e32 v143, v143
	v_mul_f32_e32 v137, 0xbfb8aa3b, v130
	v_mul_f32_e32 v136, 0xbfb8aa3b, v134
	v_exp_f32_e32 v140, v137
	v_pk_add_f32 v[142:143], v[142:143], 1.0 op_sel_hi:[1,0]
	v_mul_f32_e32 v137, 0xbfb8aa3b, v135
	v_rcp_f32_e32 v146, v143
	v_exp_f32_e32 v136, v136
	v_exp_f32_e32 v137, v137
	v_mul_f32_e32 v141, 0xbfb8aa3b, v131
	v_mul_f32_e32 v133, v133, v146
	v_rcp_f32_e32 v145, v142
	v_pk_add_f32 v[136:137], v[136:137], 1.0 op_sel_hi:[1,0]
	v_exp_f32_e32 v141, v141
	v_mul_f32_e32 v132, v132, v145
	v_rcp_f32_e32 v143, v137
	s_nop 0
	v_mul_f32_e32 v135, v135, v143
	v_rcp_f32_e32 v142, v136
	s_nop 0
	v_mul_f32_e32 v134, v134, v142
	v_mul_f32_e32 v136, 0xbfb8aa3b, v129
	v_exp_f32_e32 v145, v136
	v_pk_add_f32 v[136:137], v[140:141], 1.0 op_sel_hi:[1,0]
	v_pk_add_f32 v[140:141], v[144:145], 1.0 op_sel_hi:[1,0]
	s_nop 0
	v_rcp_f32_e32 v143, v141
	s_nop 0
	v_mul_f32_e32 v129, v129, v143
	v_rcp_f32_e32 v142, v140
	s_nop 0
	v_mul_f32_e32 v128, v128, v142
	v_rcp_f32_e32 v141, v137
	s_nop 0
	v_mul_f32_e32 v131, v131, v141
	v_rcp_f32_e32 v140, v136
	s_nop 0
	v_mul_f32_e32 v130, v130, v140

.LBB0_736:
	s_mov_b32 s0, 0x3e0293ee
	v_pk_mul_f32 v[134:135], v[128:129], s[0:1] op_sel_hi:[1,0]
	v_pk_mul_f32 v[136:137], v[126:127], s[0:1] op_sel_hi:[1,0]
	v_pk_mul_f32 v[120:121], v[124:125], s[0:1] op_sel_hi:[1,0]
	v_pk_mul_f32 v[138:139], v[122:123], s[0:1] op_sel_hi:[1,0]
	v_cndmask_b32_e64 v121, v125, v121, s[10:11]
	v_cndmask_b32_e64 v120, v124, v120, s[10:11]
	v_cndmask_b32_e64 v123, v123, v139, s[10:11]
	v_cndmask_b32_e64 v122, v122, v138, s[10:11]
	v_cndmask_b32_e64 v125, v129, v135, s[10:11]
	v_cndmask_b32_e64 v124, v128, v134, s[10:11]
	v_cndmask_b32_e64 v127, v127, v137, s[10:11]
	s_and_b64 vcc, exec, s[12:13]
	v_cndmask_b32_e64 v126, v126, v136, s[10:11]
	s_cbranch_vccnz .LBB0_738
	v_mul_f32_e32 v137, 0xbfb8aa3b, v120
	v_mul_f32_e32 v136, 0xbfb8aa3b, v124
	v_exp_f32_e32 v138, v137
	v_mul_f32_e32 v137, 0xbfb8aa3b, v125
	v_exp_f32_e32 v136, v136
	v_exp_f32_e32 v137, v137
	v_mul_f32_e32 v129, 0xbfb8aa3b, v122
	v_mul_f32_e32 v128, 0xbfb8aa3b, v126
	v_exp_f32_e32 v134, v129
	v_pk_add_f32 v[136:137], v[136:137], 1.0 op_sel_hi:[1,0]
	v_mul_f32_e32 v129, 0xbfb8aa3b, v127
	v_rcp_f32_e32 v140, v137
	v_exp_f32_e32 v128, v128
	v_exp_f32_e32 v129, v129
	v_mul_f32_e32 v135, 0xbfb8aa3b, v123
	v_mul_f32_e32 v125, v125, v140
	v_rcp_f32_e32 v139, v136
	v_pk_add_f32 v[128:129], v[128:129], 1.0 op_sel_hi:[1,0]
	v_exp_f32_e32 v135, v135
	v_mul_f32_e32 v124, v124, v139
	v_rcp_f32_e32 v137, v129
	s_nop 0
	v_mul_f32_e32 v127, v127, v137
	v_rcp_f32_e32 v136, v128
	s_nop 0
	v_mul_f32_e32 v126, v126, v136
	v_mul_f32_e32 v128, 0xbfb8aa3b, v121
	v_exp_f32_e32 v139, v128
	v_pk_add_f32 v[128:129], v[134:135], 1.0 op_sel_hi:[1,0]
	v_pk_add_f32 v[134:135], v[138:139], 1.0 op_sel_hi:[1,0]
	s_nop 0
	v_rcp_f32_e32 v137, v135
	s_nop 0
	v_mul_f32_e32 v121, v121, v137
	v_rcp_f32_e32 v136, v134
	s_nop 0
	v_mul_f32_e32 v120, v120, v136
	v_rcp_f32_e32 v135, v129
	s_nop 0
	v_mul_f32_e32 v123, v123, v135
	v_rcp_f32_e32 v134, v128
	s_nop 0
	v_mul_f32_e32 v122, v122, v134

.LBB0_748:
	s_mov_b32 s0, 0x3e0293ee
	v_pk_mul_f32 v[124:125], v[120:121], s[0:1] op_sel_hi:[1,0]
	v_pk_mul_f32 v[126:127], v[118:119], s[0:1] op_sel_hi:[1,0]
	v_pk_mul_f32 v[112:113], v[116:117], s[0:1] op_sel_hi:[1,0]
	v_pk_mul_f32 v[128:129], v[114:115], s[0:1] op_sel_hi:[1,0]
	v_cndmask_b32_e64 v113, v117, v113, s[10:11]
	v_cndmask_b32_e64 v112, v116, v112, s[10:11]
	v_cndmask_b32_e64 v115, v115, v129, s[10:11]
	v_cndmask_b32_e64 v114, v114, v128, s[10:11]
	v_cndmask_b32_e64 v117, v121, v125, s[10:11]
	v_cndmask_b32_e64 v116, v120, v124, s[10:11]
	v_cndmask_b32_e64 v119, v119, v127, s[10:11]
	s_and_b64 vcc, exec, s[12:13]
	v_cndmask_b32_e64 v118, v118, v126, s[10:11]
	s_cbranch_vccnz .LBB0_750
	v_mul_f32_e32 v127, 0xbfb8aa3b, v112
	v_mul_f32_e32 v126, 0xbfb8aa3b, v116
	v_exp_f32_e32 v128, v127
	v_mul_f32_e32 v127, 0xbfb8aa3b, v117
	v_exp_f32_e32 v126, v126
	v_exp_f32_e32 v127, v127
	v_mul_f32_e32 v121, 0xbfb8aa3b, v114
	v_mul_f32_e32 v120, 0xbfb8aa3b, v118
	v_exp_f32_e32 v124, v121
	v_pk_add_f32 v[126:127], v[126:127], 1.0 op_sel_hi:[1,0]
	v_mul_f32_e32 v121, 0xbfb8aa3b, v119
	v_rcp_f32_e32 v130, v127
	v_exp_f32_e32 v120, v120
	v_exp_f32_e32 v121, v121
	v_mul_f32_e32 v125, 0xbfb8aa3b, v115
	v_mul_f32_e32 v117, v117, v130
	v_rcp_f32_e32 v129, v126
	v_pk_add_f32 v[120:121], v[120:121], 1.0 op_sel_hi:[1,0]
	v_exp_f32_e32 v125, v125
	v_mul_f32_e32 v116, v116, v129
	v_rcp_f32_e32 v127, v121
	s_nop 0
	v_mul_f32_e32 v119, v119, v127
	v_rcp_f32_e32 v126, v120
	s_nop 0
	v_mul_f32_e32 v118, v118, v126
	v_mul_f32_e32 v120, 0xbfb8aa3b, v113
	v_exp_f32_e32 v129, v120
	v_pk_add_f32 v[120:121], v[124:125], 1.0 op_sel_hi:[1,0]
	v_pk_add_f32 v[124:125], v[128:129], 1.0 op_sel_hi:[1,0]
	s_nop 0
	v_rcp_f32_e32 v127, v125
	s_nop 0
	v_mul_f32_e32 v113, v113, v127
	v_rcp_f32_e32 v126, v124
	s_nop 0
	v_mul_f32_e32 v112, v112, v126
	v_rcp_f32_e32 v125, v121
	s_nop 0
	v_mul_f32_e32 v115, v115, v125
	v_rcp_f32_e32 v124, v120
	s_nop 0
	v_mul_f32_e32 v114, v114, v124

.LBB0_760:
	s_mov_b32 s0, 0x3e0293ee
	v_pk_mul_f32 v[106:107], v[114:115], s[0:1] op_sel_hi:[1,0]
	v_pk_mul_f32 v[120:121], v[112:113], s[0:1] op_sel_hi:[1,0]
	v_pk_mul_f32 v[100:101], v[104:105], s[0:1] op_sel_hi:[1,0]
	v_pk_mul_f32 v[122:123], v[102:103], s[0:1] op_sel_hi:[1,0]
	v_cndmask_b32_e64 v101, v105, v101, s[10:11]
	v_cndmask_b32_e64 v100, v104, v100, s[10:11]
	v_cndmask_b32_e64 v103, v103, v123, s[10:11]
	v_cndmask_b32_e64 v102, v102, v122, s[10:11]
	v_cndmask_b32_e64 v105, v115, v107, s[10:11]
	v_cndmask_b32_e64 v104, v114, v106, s[10:11]
	v_cndmask_b32_e64 v107, v113, v121, s[10:11]
	s_and_b64 vcc, exec, s[12:13]
	v_cndmask_b32_e64 v106, v112, v120, s[10:11]
	s_cbranch_vccnz .LBB0_762
	v_mul_f32_e32 v121, 0xbfb8aa3b, v100
	v_mul_f32_e32 v120, 0xbfb8aa3b, v104
	v_exp_f32_e32 v122, v121
	v_mul_f32_e32 v121, 0xbfb8aa3b, v105
	v_exp_f32_e32 v120, v120
	v_exp_f32_e32 v121, v121
	v_mul_f32_e32 v113, 0xbfb8aa3b, v102
	v_mul_f32_e32 v112, 0xbfb8aa3b, v106
	v_exp_f32_e32 v114, v113
	v_pk_add_f32 v[120:121], v[120:121], 1.0 op_sel_hi:[1,0]
	v_mul_f32_e32 v113, 0xbfb8aa3b, v107
	v_rcp_f32_e32 v124, v121
	v_exp_f32_e32 v112, v112
	v_exp_f32_e32 v113, v113
	v_mul_f32_e32 v115, 0xbfb8aa3b, v103
	v_mul_f32_e32 v105, v105, v124
	v_rcp_f32_e32 v123, v120
	v_pk_add_f32 v[112:113], v[112:113], 1.0 op_sel_hi:[1,0]
	v_exp_f32_e32 v115, v115
	v_mul_f32_e32 v104, v104, v123
	v_rcp_f32_e32 v121, v113
	s_nop 0
	v_mul_f32_e32 v107, v107, v121
	v_rcp_f32_e32 v120, v112
	s_nop 0
	v_mul_f32_e32 v106, v106, v120
	v_mul_f32_e32 v112, 0xbfb8aa3b, v101
	v_exp_f32_e32 v123, v112
	v_pk_add_f32 v[112:113], v[114:115], 1.0 op_sel_hi:[1,0]
	v_pk_add_f32 v[114:115], v[122:123], 1.0 op_sel_hi:[1,0]
	s_nop 0
	v_rcp_f32_e32 v121, v115
	s_nop 0
	v_mul_f32_e32 v101, v101, v121
	v_rcp_f32_e32 v120, v114
	s_nop 0
	v_mul_f32_e32 v100, v100, v120
	v_rcp_f32_e32 v115, v113
	s_nop 0
	v_mul_f32_e32 v103, v103, v115
	v_rcp_f32_e32 v114, v112
	s_nop 0
	v_mul_f32_e32 v102, v102, v114

.LBB0_772:
	s_mov_b32 s0, 0x3e0293ee
	v_pk_mul_f32 v[104:105], v[100:101], s[0:1] op_sel_hi:[1,0]
	v_pk_mul_f32 v[106:107], v[98:99], s[0:1] op_sel_hi:[1,0]
	v_pk_mul_f32 v[92:93], v[96:97], s[0:1] op_sel_hi:[1,0]
	v_pk_mul_f32 v[112:113], v[94:95], s[0:1] op_sel_hi:[1,0]
	v_cndmask_b32_e64 v93, v97, v93, s[10:11]
	v_cndmask_b32_e64 v92, v96, v92, s[10:11]
	v_cndmask_b32_e64 v95, v95, v113, s[10:11]
	v_cndmask_b32_e64 v94, v94, v112, s[10:11]
	v_cndmask_b32_e64 v97, v101, v105, s[10:11]
	v_cndmask_b32_e64 v96, v100, v104, s[10:11]
	v_cndmask_b32_e64 v99, v99, v107, s[10:11]
	s_and_b64 vcc, exec, s[12:13]
	v_cndmask_b32_e64 v98, v98, v106, s[10:11]
	s_cbranch_vccnz .LBB0_774
	v_mul_f32_e32 v107, 0xbfb8aa3b, v92
	v_mul_f32_e32 v106, 0xbfb8aa3b, v96
	v_exp_f32_e32 v112, v107
	v_mul_f32_e32 v107, 0xbfb8aa3b, v97
	v_exp_f32_e32 v106, v106
	v_exp_f32_e32 v107, v107
	v_mul_f32_e32 v101, 0xbfb8aa3b, v94
	v_mul_f32_e32 v100, 0xbfb8aa3b, v98
	v_exp_f32_e32 v104, v101
	v_pk_add_f32 v[106:107], v[106:107], 1.0 op_sel_hi:[1,0]
	v_mul_f32_e32 v101, 0xbfb8aa3b, v99
	v_rcp_f32_e32 v114, v107
	v_exp_f32_e32 v100, v100
	v_exp_f32_e32 v101, v101
	v_mul_f32_e32 v105, 0xbfb8aa3b, v95
	v_mul_f32_e32 v97, v97, v114
	v_rcp_f32_e32 v113, v106
	v_pk_add_f32 v[100:101], v[100:101], 1.0 op_sel_hi:[1,0]
	v_exp_f32_e32 v105, v105
	v_mul_f32_e32 v96, v96, v113
	v_rcp_f32_e32 v107, v101
	s_nop 0
	v_mul_f32_e32 v99, v99, v107
	v_rcp_f32_e32 v106, v100
	s_nop 0
	v_mul_f32_e32 v98, v98, v106
	v_mul_f32_e32 v100, 0xbfb8aa3b, v93
	v_exp_f32_e32 v113, v100
	v_pk_add_f32 v[100:101], v[104:105], 1.0 op_sel_hi:[1,0]
	v_pk_add_f32 v[104:105], v[112:113], 1.0 op_sel_hi:[1,0]
	s_nop 0
	v_rcp_f32_e32 v107, v105
	s_nop 0
	v_mul_f32_e32 v93, v93, v107
	v_rcp_f32_e32 v106, v104
	s_nop 0
	v_mul_f32_e32 v92, v92, v106
	v_rcp_f32_e32 v105, v101
	s_nop 0
	v_mul_f32_e32 v95, v95, v105
	v_rcp_f32_e32 v104, v100
	s_nop 0
	v_mul_f32_e32 v94, v94, v104

.LBB0_786:
	s_mov_b32 s0, 0x3e0293ee
	v_pk_mul_f32 v[112:113], v[92:93], s[0:1] op_sel_hi:[1,0]
	v_pk_mul_f32 v[116:117], v[90:91], s[0:1] op_sel_hi:[1,0]
	v_pk_mul_f32 v[84:85], v[88:89], s[0:1] op_sel_hi:[1,0]
	v_pk_mul_f32 v[118:119], v[86:87], s[0:1] op_sel_hi:[1,0]
	v_cndmask_b32_e64 v85, v89, v85, s[10:11]
	v_cndmask_b32_e64 v84, v88, v84, s[10:11]
	v_cndmask_b32_e64 v87, v87, v119, s[10:11]
	v_cndmask_b32_e64 v86, v86, v118, s[10:11]
	v_cndmask_b32_e64 v89, v93, v113, s[10:11]
	v_cndmask_b32_e64 v88, v92, v112, s[10:11]
	v_cndmask_b32_e64 v91, v91, v117, s[10:11]
	s_and_b64 vcc, exec, s[12:13]
	v_cndmask_b32_e64 v90, v90, v116, s[10:11]
	s_cbranch_vccnz .LBB0_788
	v_mul_f32_e32 v95, 0xbfb8aa3b, v87
	v_exp_f32_e32 v113, v95
	v_mul_f32_e32 v95, 0xbfb8aa3b, v88
	v_exp_f32_e32 v116, v95
	v_mul_f32_e32 v95, 0xbfb8aa3b, v84
	v_exp_f32_e32 v118, v95
	v_mul_f32_e32 v95, 0xbfb8aa3b, v89
	v_exp_f32_e32 v117, v95
	v_mul_f32_e32 v93, 0xbfb8aa3b, v86
	v_mul_f32_e32 v92, 0xbfb8aa3b, v90
	v_exp_f32_e32 v112, v93
	v_pk_add_f32 v[116:117], v[116:117], 1.0 op_sel_hi:[1,0]
	v_mul_f32_e32 v93, 0xbfb8aa3b, v91
	v_rcp_f32_e32 v99, v117
	v_exp_f32_e32 v92, v92
	v_exp_f32_e32 v93, v93
	v_mul_f32_e32 v89, v89, v99
	v_rcp_f32_e32 v99, v116
	v_pk_add_f32 v[92:93], v[92:93], 1.0 op_sel_hi:[1,0]
	v_mul_f32_e32 v88, v88, v99
	v_rcp_f32_e32 v99, v93
	s_nop 0
	v_mul_f32_e32 v91, v91, v99
	v_rcp_f32_e32 v95, v92
	s_nop 0
	v_mul_f32_e32 v90, v90, v95
	v_mul_f32_e32 v92, 0xbfb8aa3b, v85
	v_exp_f32_e32 v119, v92
	v_pk_add_f32 v[92:93], v[112:113], 1.0 op_sel_hi:[1,0]
	v_pk_add_f32 v[112:113], v[118:119], 1.0 op_sel_hi:[1,0]
	s_nop 0
	v_rcp_f32_e32 v99, v113
	s_nop 0
	v_mul_f32_e32 v85, v85, v99
	v_rcp_f32_e32 v99, v112
	s_nop 0
	v_mul_f32_e32 v84, v84, v99
	v_rcp_f32_e32 v99, v93
	s_nop 0
	v_mul_f32_e32 v87, v87, v99
	v_rcp_f32_e32 v95, v92
	s_nop 0
	v_mul_f32_e32 v86, v86, v95

.LBB0_798:
	s_mov_b32 s0, 0x3e0293ee
	v_pk_mul_f32 v[88:89], v[84:85], s[0:1] op_sel_hi:[1,0]
	v_pk_mul_f32 v[90:91], v[82:83], s[0:1] op_sel_hi:[1,0]
	v_pk_mul_f32 v[76:77], v[80:81], s[0:1] op_sel_hi:[1,0]
	v_pk_mul_f32 v[92:93], v[78:79], s[0:1] op_sel_hi:[1,0]
	v_cndmask_b32_e64 v77, v81, v77, s[10:11]
	v_cndmask_b32_e64 v76, v80, v76, s[10:11]
	v_cndmask_b32_e64 v79, v79, v93, s[10:11]
	v_cndmask_b32_e64 v78, v78, v92, s[10:11]
	v_cndmask_b32_e64 v81, v85, v89, s[10:11]
	v_cndmask_b32_e64 v80, v84, v88, s[10:11]
	v_cndmask_b32_e64 v83, v83, v91, s[10:11]
	s_and_b64 vcc, exec, s[12:13]
	v_cndmask_b32_e64 v82, v82, v90, s[10:11]
	s_cbranch_vccnz .LBB0_800
	v_mul_f32_e32 v91, 0xbfb8aa3b, v76
	v_mul_f32_e32 v90, 0xbfb8aa3b, v80
	v_exp_f32_e32 v92, v91
	v_mul_f32_e32 v91, 0xbfb8aa3b, v81
	v_exp_f32_e32 v90, v90
	v_exp_f32_e32 v91, v91
	v_mul_f32_e32 v85, 0xbfb8aa3b, v78
	v_mul_f32_e32 v84, 0xbfb8aa3b, v82
	v_exp_f32_e32 v88, v85
	v_pk_add_f32 v[90:91], v[90:91], 1.0 op_sel_hi:[1,0]
	v_mul_f32_e32 v85, 0xbfb8aa3b, v83
	v_rcp_f32_e32 v101, v91
	v_exp_f32_e32 v84, v84
	v_exp_f32_e32 v85, v85
	v_mul_f32_e32 v89, 0xbfb8aa3b, v79
	v_mul_f32_e32 v81, v81, v101
	v_rcp_f32_e32 v93, v90
	v_pk_add_f32 v[84:85], v[84:85], 1.0 op_sel_hi:[1,0]
	v_exp_f32_e32 v89, v89
	v_mul_f32_e32 v80, v80, v93
	v_rcp_f32_e32 v91, v85
	s_nop 0
	v_mul_f32_e32 v83, v83, v91
	v_rcp_f32_e32 v90, v84
	s_nop 0
	v_mul_f32_e32 v82, v82, v90
	v_mul_f32_e32 v84, 0xbfb8aa3b, v77
	v_exp_f32_e32 v93, v84
	v_pk_add_f32 v[84:85], v[88:89], 1.0 op_sel_hi:[1,0]
	v_pk_add_f32 v[88:89], v[92:93], 1.0 op_sel_hi:[1,0]
	s_nop 0
	v_rcp_f32_e32 v91, v89
	s_nop 0
	v_mul_f32_e32 v77, v77, v91
	v_rcp_f32_e32 v90, v88
	s_nop 0
	v_mul_f32_e32 v76, v76, v90
	v_rcp_f32_e32 v89, v85
	s_nop 0
	v_mul_f32_e32 v79, v79, v89
	v_rcp_f32_e32 v88, v84
	s_nop 0
	v_mul_f32_e32 v78, v78, v88

.LBB0_810:
	s_mov_b32 s0, 0x3e0293ee
	v_pk_mul_f32 v[82:83], v[76:77], s[0:1] op_sel_hi:[1,0]
	v_pk_mul_f32 v[86:87], v[74:75], s[0:1] op_sel_hi:[1,0]
	v_pk_mul_f32 v[68:69], v[72:73], s[0:1] op_sel_hi:[1,0]
	v_pk_mul_f32 v[88:89], v[70:71], s[0:1] op_sel_hi:[1,0]
	v_cndmask_b32_e64 v69, v73, v69, s[10:11]
	v_cndmask_b32_e64 v68, v72, v68, s[10:11]
	v_cndmask_b32_e64 v71, v71, v89, s[10:11]
	v_cndmask_b32_e64 v70, v70, v88, s[10:11]
	v_cndmask_b32_e64 v73, v77, v83, s[10:11]
	v_cndmask_b32_e64 v72, v76, v82, s[10:11]
	v_cndmask_b32_e64 v75, v75, v87, s[10:11]
	s_and_b64 vcc, exec, s[12:13]
	v_cndmask_b32_e64 v74, v74, v86, s[10:11]
	s_cbranch_vccnz .LBB0_812
	v_mul_f32_e32 v85, 0xbfb8aa3b, v72
	v_exp_f32_e32 v86, v85
	v_mul_f32_e32 v85, 0xbfb8aa3b, v68
	v_exp_f32_e32 v88, v85
	v_mul_f32_e32 v85, 0xbfb8aa3b, v73
	v_exp_f32_e32 v87, v85
	v_mul_f32_e32 v77, 0xbfb8aa3b, v70
	v_mul_f32_e32 v76, 0xbfb8aa3b, v74
	v_exp_f32_e32 v82, v77
	v_pk_add_f32 v[86:87], v[86:87], 1.0 op_sel_hi:[1,0]
	v_mul_f32_e32 v77, 0xbfb8aa3b, v75
	v_rcp_f32_e32 v89, v87
	v_exp_f32_e32 v76, v76
	v_exp_f32_e32 v77, v77
	v_mul_f32_e32 v83, 0xbfb8aa3b, v71
	v_mul_f32_e32 v73, v73, v89
	v_rcp_f32_e32 v87, v86
	v_pk_add_f32 v[76:77], v[76:77], 1.0 op_sel_hi:[1,0]
	v_exp_f32_e32 v83, v83
	v_mul_f32_e32 v72, v72, v87
	v_rcp_f32_e32 v86, v77
	s_nop 0
	v_mul_f32_e32 v75, v75, v86
	v_rcp_f32_e32 v85, v76
	s_nop 0
	v_mul_f32_e32 v74, v74, v85
	v_mul_f32_e32 v76, 0xbfb8aa3b, v69
	v_exp_f32_e32 v89, v76
	v_pk_add_f32 v[76:77], v[82:83], 1.0 op_sel_hi:[1,0]
	v_pk_add_f32 v[82:83], v[88:89], 1.0 op_sel_hi:[1,0]
	s_nop 0
	v_rcp_f32_e32 v86, v83
	s_nop 0
	v_mul_f32_e32 v69, v69, v86
	v_rcp_f32_e32 v85, v82
	s_nop 0
	v_mul_f32_e32 v68, v68, v85
	v_rcp_f32_e32 v83, v77
	s_nop 0
	v_mul_f32_e32 v71, v71, v83
	v_rcp_f32_e32 v82, v76
	s_nop 0
	v_mul_f32_e32 v70, v70, v82

.LBB0_822:
	s_mov_b32 s0, 0x3e0293ee
	v_pk_mul_f32 v[72:73], v[68:69], s[0:1] op_sel_hi:[1,0]
	v_pk_mul_f32 v[74:75], v[66:67], s[0:1] op_sel_hi:[1,0]
	v_pk_mul_f32 v[60:61], v[64:65], s[0:1] op_sel_hi:[1,0]
	v_pk_mul_f32 v[76:77], v[62:63], s[0:1] op_sel_hi:[1,0]
	v_cndmask_b32_e64 v61, v65, v61, s[10:11]
	v_cndmask_b32_e64 v60, v64, v60, s[10:11]
	v_cndmask_b32_e64 v63, v63, v77, s[10:11]
	v_cndmask_b32_e64 v62, v62, v76, s[10:11]
	v_cndmask_b32_e64 v65, v69, v73, s[10:11]
	v_cndmask_b32_e64 v64, v68, v72, s[10:11]
	v_cndmask_b32_e64 v67, v67, v75, s[10:11]
	s_and_b64 vcc, exec, s[12:13]
	v_cndmask_b32_e64 v66, v66, v74, s[10:11]
	s_cbranch_vccnz .LBB0_824
	v_mul_f32_e32 v75, 0xbfb8aa3b, v60
	v_mul_f32_e32 v74, 0xbfb8aa3b, v64
	v_exp_f32_e32 v76, v75
	v_mul_f32_e32 v75, 0xbfb8aa3b, v65
	v_exp_f32_e32 v74, v74
	v_exp_f32_e32 v75, v75
	v_mul_f32_e32 v69, 0xbfb8aa3b, v62
	v_mul_f32_e32 v68, 0xbfb8aa3b, v66
	v_exp_f32_e32 v72, v69
	v_pk_add_f32 v[74:75], v[74:75], 1.0 op_sel_hi:[1,0]
	v_mul_f32_e32 v69, 0xbfb8aa3b, v67
	v_rcp_f32_e32 v78, v75
	v_exp_f32_e32 v68, v68
	v_exp_f32_e32 v69, v69
	v_mul_f32_e32 v73, 0xbfb8aa3b, v63
	v_mul_f32_e32 v65, v65, v78
	v_rcp_f32_e32 v77, v74
	v_pk_add_f32 v[68:69], v[68:69], 1.0 op_sel_hi:[1,0]
	v_exp_f32_e32 v73, v73
	v_mul_f32_e32 v64, v64, v77
	v_rcp_f32_e32 v75, v69
	s_nop 0
	v_mul_f32_e32 v67, v67, v75
	v_rcp_f32_e32 v74, v68
	s_nop 0
	v_mul_f32_e32 v66, v66, v74
	v_mul_f32_e32 v68, 0xbfb8aa3b, v61
	v_exp_f32_e32 v77, v68
	v_pk_add_f32 v[68:69], v[72:73], 1.0 op_sel_hi:[1,0]
	v_pk_add_f32 v[72:73], v[76:77], 1.0 op_sel_hi:[1,0]
	s_nop 0
	v_rcp_f32_e32 v75, v73
	s_nop 0
	v_mul_f32_e32 v61, v61, v75
	v_rcp_f32_e32 v74, v72
	s_nop 0
	v_mul_f32_e32 v60, v60, v74
	v_rcp_f32_e32 v73, v69
	s_nop 0
	v_mul_f32_e32 v63, v63, v73
	v_rcp_f32_e32 v72, v68
	s_nop 0
	v_mul_f32_e32 v62, v62, v72

.LBB0_834:
	s_mov_b32 s0, 0x3e0293ee
	v_pk_mul_f32 v[66:67], v[60:61], s[0:1] op_sel_hi:[1,0]
	v_pk_mul_f32 v[70:71], v[58:59], s[0:1] op_sel_hi:[1,0]
	v_pk_mul_f32 v[52:53], v[56:57], s[0:1] op_sel_hi:[1,0]
	v_pk_mul_f32 v[72:73], v[54:55], s[0:1] op_sel_hi:[1,0]
	v_cndmask_b32_e64 v53, v57, v53, s[10:11]
	v_cndmask_b32_e64 v52, v56, v52, s[10:11]
	v_cndmask_b32_e64 v55, v55, v73, s[10:11]
	v_cndmask_b32_e64 v54, v54, v72, s[10:11]
	v_cndmask_b32_e64 v57, v61, v67, s[10:11]
	v_cndmask_b32_e64 v56, v60, v66, s[10:11]
	v_cndmask_b32_e64 v59, v59, v71, s[10:11]
	s_and_b64 vcc, exec, s[12:13]
	v_cndmask_b32_e64 v58, v58, v70, s[10:11]
	s_cbranch_vccnz .LBB0_836
	v_mul_f32_e32 v69, 0xbfb8aa3b, v56
	v_exp_f32_e32 v70, v69
	v_mul_f32_e32 v69, 0xbfb8aa3b, v52
	v_exp_f32_e32 v72, v69
	v_mul_f32_e32 v69, 0xbfb8aa3b, v57
	v_exp_f32_e32 v71, v69
	v_mul_f32_e32 v61, 0xbfb8aa3b, v54
	v_mul_f32_e32 v60, 0xbfb8aa3b, v58
	v_exp_f32_e32 v66, v61
	v_pk_add_f32 v[70:71], v[70:71], 1.0 op_sel_hi:[1,0]
	v_mul_f32_e32 v61, 0xbfb8aa3b, v59
	v_rcp_f32_e32 v73, v71
	v_exp_f32_e32 v60, v60
	v_exp_f32_e32 v61, v61
	v_mul_f32_e32 v67, 0xbfb8aa3b, v55
	v_mul_f32_e32 v57, v57, v73
	v_rcp_f32_e32 v71, v70
	v_pk_add_f32 v[60:61], v[60:61], 1.0 op_sel_hi:[1,0]
	v_exp_f32_e32 v67, v67
	v_mul_f32_e32 v56, v56, v71
	v_rcp_f32_e32 v70, v61
	s_nop 0
	v_mul_f32_e32 v59, v59, v70
	v_rcp_f32_e32 v69, v60
	s_nop 0
	v_mul_f32_e32 v58, v58, v69
	v_mul_f32_e32 v60, 0xbfb8aa3b, v53
	v_exp_f32_e32 v73, v60
	v_pk_add_f32 v[60:61], v[66:67], 1.0 op_sel_hi:[1,0]
	v_pk_add_f32 v[66:67], v[72:73], 1.0 op_sel_hi:[1,0]
	s_nop 0
	v_rcp_f32_e32 v70, v67
	s_nop 0
	v_mul_f32_e32 v53, v53, v70
	v_rcp_f32_e32 v69, v66
	s_nop 0
	v_mul_f32_e32 v52, v52, v69
	v_rcp_f32_e32 v67, v61
	s_nop 0
	v_mul_f32_e32 v55, v55, v67
	v_rcp_f32_e32 v66, v60
	s_nop 0
	v_mul_f32_e32 v54, v54, v66

.LBB0_846:
	s_mov_b32 s0, 0x3e0293ee
	v_pk_mul_f32 v[56:57], v[52:53], s[0:1] op_sel_hi:[1,0]
	v_pk_mul_f32 v[58:59], v[50:51], s[0:1] op_sel_hi:[1,0]
	v_pk_mul_f32 v[44:45], v[48:49], s[0:1] op_sel_hi:[1,0]
	v_pk_mul_f32 v[60:61], v[46:47], s[0:1] op_sel_hi:[1,0]
	v_cndmask_b32_e64 v45, v49, v45, s[10:11]
	v_cndmask_b32_e64 v44, v48, v44, s[10:11]
	v_cndmask_b32_e64 v47, v47, v61, s[10:11]
	v_cndmask_b32_e64 v46, v46, v60, s[10:11]
	v_cndmask_b32_e64 v49, v53, v57, s[10:11]
	v_cndmask_b32_e64 v48, v52, v56, s[10:11]
	v_cndmask_b32_e64 v51, v51, v59, s[10:11]
	s_and_b64 vcc, exec, s[12:13]
	v_cndmask_b32_e64 v50, v50, v58, s[10:11]
	s_cbranch_vccnz .LBB0_848
	v_mul_f32_e32 v59, 0xbfb8aa3b, v44
	v_mul_f32_e32 v58, 0xbfb8aa3b, v48
	v_exp_f32_e32 v60, v59
	v_mul_f32_e32 v59, 0xbfb8aa3b, v49
	v_exp_f32_e32 v58, v58
	v_exp_f32_e32 v59, v59
	v_mul_f32_e32 v53, 0xbfb8aa3b, v46
	v_mul_f32_e32 v52, 0xbfb8aa3b, v50
	v_exp_f32_e32 v56, v53
	v_pk_add_f32 v[58:59], v[58:59], 1.0 op_sel_hi:[1,0]
	v_mul_f32_e32 v53, 0xbfb8aa3b, v51
	v_rcp_f32_e32 v62, v59
	v_exp_f32_e32 v52, v52
	v_exp_f32_e32 v53, v53
	v_mul_f32_e32 v57, 0xbfb8aa3b, v47
	v_mul_f32_e32 v49, v49, v62
	v_rcp_f32_e32 v61, v58
	v_pk_add_f32 v[52:53], v[52:53], 1.0 op_sel_hi:[1,0]
	v_exp_f32_e32 v57, v57
	v_mul_f32_e32 v48, v48, v61
	v_rcp_f32_e32 v59, v53
	s_nop 0
	v_mul_f32_e32 v51, v51, v59
	v_rcp_f32_e32 v58, v52
	s_nop 0
	v_mul_f32_e32 v50, v50, v58
	v_mul_f32_e32 v52, 0xbfb8aa3b, v45
	v_exp_f32_e32 v61, v52
	v_pk_add_f32 v[52:53], v[56:57], 1.0 op_sel_hi:[1,0]
	v_pk_add_f32 v[56:57], v[60:61], 1.0 op_sel_hi:[1,0]
	s_nop 0
	v_rcp_f32_e32 v59, v57
	s_nop 0
	v_mul_f32_e32 v45, v45, v59
	v_rcp_f32_e32 v58, v56
	s_nop 0
	v_mul_f32_e32 v44, v44, v58
	v_rcp_f32_e32 v57, v53
	s_nop 0
	v_mul_f32_e32 v47, v47, v57
	v_rcp_f32_e32 v56, v52
	s_nop 0
	v_mul_f32_e32 v46, v46, v56

.LBB0_858:
	s_mov_b32 s0, 0x3e0293ee
	v_pk_mul_f32 v[14:15], v[46:47], s[0:1] op_sel_hi:[1,0]
	v_pk_mul_f32 v[52:53], v[44:45], s[0:1] op_sel_hi:[1,0]
	v_pk_mul_f32 v[8:9], v[12:13], s[0:1] op_sel_hi:[1,0]
	v_pk_mul_f32 v[56:57], v[10:11], s[0:1] op_sel_hi:[1,0]
	v_cndmask_b32_e64 v9, v13, v9, s[10:11]
	v_cndmask_b32_e64 v8, v12, v8, s[10:11]
	v_cndmask_b32_e64 v11, v11, v57, s[10:11]
	v_cndmask_b32_e64 v10, v10, v56, s[10:11]
	v_cndmask_b32_e64 v13, v47, v15, s[10:11]
	v_cndmask_b32_e64 v12, v46, v14, s[10:11]
	v_cndmask_b32_e64 v15, v45, v53, s[10:11]
	s_and_b64 vcc, exec, s[12:13]
	v_cndmask_b32_e64 v14, v44, v52, s[10:11]
	s_cbranch_vccnz .LBB0_860
	v_mul_f32_e32 v53, 0xbfb8aa3b, v8
	v_mul_f32_e32 v52, 0xbfb8aa3b, v12
	v_exp_f32_e32 v56, v53
	v_mul_f32_e32 v53, 0xbfb8aa3b, v13
	v_exp_f32_e32 v52, v52
	v_exp_f32_e32 v53, v53
	v_mul_f32_e32 v45, 0xbfb8aa3b, v10
	v_mul_f32_e32 v44, 0xbfb8aa3b, v14
	v_exp_f32_e32 v46, v45
	v_pk_add_f32 v[52:53], v[52:53], 1.0 op_sel_hi:[1,0]
	v_mul_f32_e32 v45, 0xbfb8aa3b, v15
	v_rcp_f32_e32 v57, v53
	v_exp_f32_e32 v44, v44
	v_exp_f32_e32 v45, v45
	v_mul_f32_e32 v47, 0xbfb8aa3b, v11
	v_mul_f32_e32 v13, v13, v57
	v_rcp_f32_e32 v55, v52
	v_pk_add_f32 v[44:45], v[44:45], 1.0 op_sel_hi:[1,0]
	v_exp_f32_e32 v47, v47
	v_mul_f32_e32 v12, v12, v55
	v_rcp_f32_e32 v53, v45
	s_nop 0
	v_mul_f32_e32 v15, v15, v53
	v_rcp_f32_e32 v52, v44
	s_nop 0
	v_mul_f32_e32 v14, v14, v52
	v_mul_f32_e32 v44, 0xbfb8aa3b, v9
	v_exp_f32_e32 v57, v44
	v_pk_add_f32 v[44:45], v[46:47], 1.0 op_sel_hi:[1,0]
	v_pk_add_f32 v[46:47], v[56:57], 1.0 op_sel_hi:[1,0]
	s_nop 0
	v_rcp_f32_e32 v53, v47
	s_nop 0
	v_mul_f32_e32 v9, v9, v53
	v_rcp_f32_e32 v52, v46
	s_nop 0
	v_mul_f32_e32 v8, v8, v52
	v_rcp_f32_e32 v47, v45
	s_nop 0
	v_mul_f32_e32 v11, v11, v47
	v_rcp_f32_e32 v46, v44
	s_nop 0
	v_mul_f32_e32 v10, v10, v46

.LBB0_870:
	s_mov_b32 s0, 0x3e0293ee
	v_pk_mul_f32 v[4:5], v[8:9], s[0:1] op_sel_hi:[1,0]
	v_pk_mul_f32 v[12:13], v[6:7], s[0:1] op_sel_hi:[1,0]
	v_pk_mul_f32 v[14:15], v[2:3], s[0:1] op_sel_hi:[1,0]
	v_pk_mul_f32 v[44:45], v[0:1], s[0:1] op_sel_hi:[1,0]
	v_cndmask_b32_e64 v3, v3, v15, s[10:11]
	v_cndmask_b32_e64 v2, v2, v14, s[10:11]
	v_cndmask_b32_e64 v1, v1, v45, s[10:11]
	v_cndmask_b32_e64 v0, v0, v44, s[10:11]
	v_cndmask_b32_e64 v5, v9, v5, s[10:11]
	v_cndmask_b32_e64 v4, v8, v4, s[10:11]
	v_cndmask_b32_e64 v7, v7, v13, s[10:11]
	s_and_b64 vcc, exec, s[12:13]
	v_cndmask_b32_e64 v6, v6, v12, s[10:11]
	s_cbranch_vccnz .LBB0_872
	v_mul_f32_e32 v15, 0xbfb8aa3b, v2
	v_mul_f32_e32 v14, 0xbfb8aa3b, v4
	v_exp_f32_e32 v44, v15
	v_mul_f32_e32 v15, 0xbfb8aa3b, v5
	v_exp_f32_e32 v14, v14
	v_exp_f32_e32 v15, v15
	v_mul_f32_e32 v9, 0xbfb8aa3b, v0
	v_mul_f32_e32 v8, 0xbfb8aa3b, v6
	v_exp_f32_e32 v12, v9
	v_pk_add_f32 v[14:15], v[14:15], 1.0 op_sel_hi:[1,0]
	v_mul_f32_e32 v9, 0xbfb8aa3b, v7
	v_rcp_f32_e32 v46, v15
	v_exp_f32_e32 v8, v8
	v_exp_f32_e32 v9, v9
	v_mul_f32_e32 v13, 0xbfb8aa3b, v1
	v_mul_f32_e32 v5, v5, v46
	v_rcp_f32_e32 v45, v14
	v_pk_add_f32 v[8:9], v[8:9], 1.0 op_sel_hi:[1,0]
	v_exp_f32_e32 v13, v13
	v_mul_f32_e32 v4, v4, v45
	v_rcp_f32_e32 v15, v9
	s_nop 0
	v_mul_f32_e32 v7, v7, v15
	v_rcp_f32_e32 v14, v8
	s_nop 0
	v_mul_f32_e32 v6, v6, v14
	v_mul_f32_e32 v8, 0xbfb8aa3b, v3
	v_exp_f32_e32 v45, v8
	v_pk_add_f32 v[8:9], v[12:13], 1.0 op_sel_hi:[1,0]
	v_pk_add_f32 v[12:13], v[44:45], 1.0 op_sel_hi:[1,0]
	s_nop 0
	v_rcp_f32_e32 v15, v13
	s_nop 0
	v_mul_f32_e32 v3, v3, v15
	v_rcp_f32_e32 v14, v12
	s_nop 0
	v_mul_f32_e32 v2, v2, v14
	v_rcp_f32_e32 v13, v9
	s_nop 0
	v_mul_f32_e32 v1, v1, v13
	v_rcp_f32_e32 v12, v8
	s_nop 0
	v_mul_f32_e32 v0, v0, v12
